# stack + W_IN sigmoid packed mul/add, GU SwiGLU epilogue batched (no trans nops, packed), MERGE epilogue 4 gate loads in flight per row + no self-max canonicalise
# speedup vs baseline: 1.0210x; 1.0061x over previous
.LBB0_209:
	s_cmp_gt_i32 s6, 9
	v_mbcnt_lo_u32_b32 v144, -1, 0
	v_mbcnt_hi_u32_b32 v144, -1, v144
	s_cselect_b64 s[20:21], -1, 0
	s_cmp_lt_i32 s6, 10
	s_cbranch_scc1 .LBB0_211
	s_mov_b32 s98, 0xbfb8aa3b
	v_pk_mul_f32 v[126:127], v[126:127], s[98:99] op_sel_hi:[1,0]
	v_pk_mul_f32 v[128:129], v[128:129], s[98:99] op_sel_hi:[1,0]
	v_pk_mul_f32 v[122:123], v[122:123], s[98:99] op_sel_hi:[1,0]
	v_pk_mul_f32 v[124:125], v[124:125], s[98:99] op_sel_hi:[1,0]
	v_exp_f32_e32 v126, v126
	v_exp_f32_e32 v127, v127
	v_exp_f32_e32 v128, v128
	v_exp_f32_e32 v129, v129
	v_exp_f32_e32 v122, v122
	v_exp_f32_e32 v123, v123
	v_exp_f32_e32 v124, v124
	v_exp_f32_e32 v125, v125
	v_pk_add_f32 v[126:127], v[126:127], 1.0 op_sel_hi:[1,0]
	v_pk_add_f32 v[128:129], v[128:129], 1.0 op_sel_hi:[1,0]
	v_pk_add_f32 v[122:123], v[122:123], 1.0 op_sel_hi:[1,0]
	v_pk_add_f32 v[124:125], v[124:125], 1.0 op_sel_hi:[1,0]
	v_rcp_f32_e32 v126, v126
	v_rcp_f32_e32 v127, v127
	v_rcp_f32_e32 v128, v128
	v_rcp_f32_e32 v129, v129
	v_rcp_f32_e32 v122, v122
	v_rcp_f32_e32 v123, v123
	v_rcp_f32_e32 v124, v124
	v_rcp_f32_e32 v125, v125
.LBB0_211:
	v_and_or_b32 v145, v144, 15, s39
	v_ashrrev_i32_e32 v144, 1, v144
	s_lshl_b32 s6, s6, 8
	v_and_b32_e32 v149, -8, v144
	v_lshl_add_u32 v148, s47, 8, v145
	v_mov_b64_e32 v[144:145], s[8:9]
	s_or_b32 s6, s6, s40
	v_mad_i64_i32 v[150:151], s[24:25], v148, s85, v[144:145]
	v_add_u32_e32 v144, s6, v149
	v_cvt_pk_bf16_f32 v126, v126, v127
	v_cvt_pk_bf16_f32 v127, v128, v129
	v_cvt_pk_bf16_f32 v129, v124, v125
	v_ashrrev_i32_e32 v145, 31, v144
	v_cndmask_b32_e64 v124, 0, 1, s[20:21]
	v_cvt_pk_bf16_f32 v128, v122, v123
	v_lshl_add_u64 v[122:123], v[144:145], 1, v[150:151]
	v_cmp_ne_u32_e64 s[6:7], 1, v124
	s_andn2_b64 vcc, exec, s[20:21]
	global_store_dwordx4 v[122:123], v[126:129], off
	s_cbranch_vccnz .LBB0_213
	s_mov_b32 s98, 0xbfb8aa3b
	v_pk_mul_f32 v[118:119], v[118:119], s[98:99] op_sel_hi:[1,0]
	v_pk_mul_f32 v[120:121], v[120:121], s[98:99] op_sel_hi:[1,0]
	v_pk_mul_f32 v[114:115], v[114:115], s[98:99] op_sel_hi:[1,0]
	v_pk_mul_f32 v[116:117], v[116:117], s[98:99] op_sel_hi:[1,0]
	v_exp_f32_e32 v118, v118
	v_exp_f32_e32 v119, v119
	v_exp_f32_e32 v120, v120
	v_exp_f32_e32 v121, v121
	v_exp_f32_e32 v114, v114
	v_exp_f32_e32 v115, v115
	v_exp_f32_e32 v116, v116
	v_exp_f32_e32 v117, v117
	v_pk_add_f32 v[118:119], v[118:119], 1.0 op_sel_hi:[1,0]
	v_pk_add_f32 v[120:121], v[120:121], 1.0 op_sel_hi:[1,0]
	v_pk_add_f32 v[114:115], v[114:115], 1.0 op_sel_hi:[1,0]
	v_pk_add_f32 v[116:117], v[116:117], 1.0 op_sel_hi:[1,0]
	v_rcp_f32_e32 v118, v118
	v_rcp_f32_e32 v119, v119
	v_rcp_f32_e32 v120, v120
	v_rcp_f32_e32 v121, v121
	v_rcp_f32_e32 v114, v114
	v_rcp_f32_e32 v115, v115
	v_rcp_f32_e32 v116, v116
	v_rcp_f32_e32 v117, v117
.LBB0_213:
	s_and_b64 vcc, exec, s[6:7]
	v_cvt_pk_bf16_f32 v118, v118, v119
	v_cvt_pk_bf16_f32 v119, v120, v121
	v_cvt_pk_bf16_f32 v120, v114, v115
	v_cvt_pk_bf16_f32 v121, v116, v117
	global_store_dwordx4 v[122:123], v[118:121], off offset:256
	s_cbranch_vccnz .LBB0_215
	s_mov_b32 s98, 0xbfb8aa3b
	v_pk_mul_f32 v[110:111], v[110:111], s[98:99] op_sel_hi:[1,0]
	v_pk_mul_f32 v[112:113], v[112:113], s[98:99] op_sel_hi:[1,0]
	v_pk_mul_f32 v[106:107], v[106:107], s[98:99] op_sel_hi:[1,0]
	v_pk_mul_f32 v[108:109], v[108:109], s[98:99] op_sel_hi:[1,0]
	v_exp_f32_e32 v110, v110
	v_exp_f32_e32 v111, v111
	v_exp_f32_e32 v112, v112
	v_exp_f32_e32 v113, v113
	v_exp_f32_e32 v106, v106
	v_exp_f32_e32 v107, v107
	v_exp_f32_e32 v108, v108
	v_exp_f32_e32 v109, v109
	v_pk_add_f32 v[110:111], v[110:111], 1.0 op_sel_hi:[1,0]
	v_pk_add_f32 v[112:113], v[112:113], 1.0 op_sel_hi:[1,0]
	v_pk_add_f32 v[106:107], v[106:107], 1.0 op_sel_hi:[1,0]
	v_pk_add_f32 v[108:109], v[108:109], 1.0 op_sel_hi:[1,0]
	v_rcp_f32_e32 v110, v110
	v_rcp_f32_e32 v111, v111
	v_rcp_f32_e32 v112, v112
	v_rcp_f32_e32 v113, v113
	v_rcp_f32_e32 v106, v106
	v_rcp_f32_e32 v107, v107
	v_rcp_f32_e32 v108, v108
	v_rcp_f32_e32 v109, v109
.LBB0_215:
	v_or_b32_e32 v116, 16, v148
	v_mov_b64_e32 v[114:115], s[8:9]
	v_mad_i64_i32 v[114:115], s[20:21], v116, s85, v[114:115]
	v_cvt_pk_bf16_f32 v110, v110, v111
	v_cvt_pk_bf16_f32 v111, v112, v113
	v_cvt_pk_bf16_f32 v112, v106, v107
	v_lshl_add_u64 v[106:107], v[144:145], 1, v[114:115]
	s_and_b64 vcc, exec, s[6:7]
	v_cvt_pk_bf16_f32 v113, v108, v109
	global_store_dwordx4 v[106:107], v[110:113], off
	s_cbranch_vccnz .LBB0_217
	s_mov_b32 s98, 0xbfb8aa3b
	v_pk_mul_f32 v[102:103], v[102:103], s[98:99] op_sel_hi:[1,0]
	v_pk_mul_f32 v[104:105], v[104:105], s[98:99] op_sel_hi:[1,0]
	v_pk_mul_f32 v[98:99], v[98:99], s[98:99] op_sel_hi:[1,0]
	v_pk_mul_f32 v[100:101], v[100:101], s[98:99] op_sel_hi:[1,0]
	v_exp_f32_e32 v102, v102
	v_exp_f32_e32 v103, v103
	v_exp_f32_e32 v104, v104
	v_exp_f32_e32 v105, v105
	v_exp_f32_e32 v98, v98
	v_exp_f32_e32 v99, v99
	v_exp_f32_e32 v100, v100
	v_exp_f32_e32 v101, v101
	v_pk_add_f32 v[102:103], v[102:103], 1.0 op_sel_hi:[1,0]
	v_pk_add_f32 v[104:105], v[104:105], 1.0 op_sel_hi:[1,0]
	v_pk_add_f32 v[98:99], v[98:99], 1.0 op_sel_hi:[1,0]
	v_pk_add_f32 v[100:101], v[100:101], 1.0 op_sel_hi:[1,0]
	v_rcp_f32_e32 v102, v102
	v_rcp_f32_e32 v103, v103
	v_rcp_f32_e32 v104, v104
	v_rcp_f32_e32 v105, v105
	v_rcp_f32_e32 v98, v98
	v_rcp_f32_e32 v99, v99
	v_rcp_f32_e32 v100, v100
	v_rcp_f32_e32 v101, v101
.LBB0_217:
	s_and_b64 vcc, exec, s[6:7]
	v_cvt_pk_bf16_f32 v102, v102, v103
	v_cvt_pk_bf16_f32 v103, v104, v105
	v_cvt_pk_bf16_f32 v104, v98, v99
	v_cvt_pk_bf16_f32 v105, v100, v101
	global_store_dwordx4 v[106:107], v[102:105], off offset:256
	s_cbranch_vccnz .LBB0_219
	s_mov_b32 s98, 0xbfb8aa3b
	v_pk_mul_f32 v[94:95], v[94:95], s[98:99] op_sel_hi:[1,0]
	v_pk_mul_f32 v[96:97], v[96:97], s[98:99] op_sel_hi:[1,0]
	v_pk_mul_f32 v[90:91], v[90:91], s[98:99] op_sel_hi:[1,0]
	v_pk_mul_f32 v[92:93], v[92:93], s[98:99] op_sel_hi:[1,0]
	v_exp_f32_e32 v94, v94
	v_exp_f32_e32 v95, v95
	v_exp_f32_e32 v96, v96
	v_exp_f32_e32 v97, v97
	v_exp_f32_e32 v90, v90
	v_exp_f32_e32 v91, v91
	v_exp_f32_e32 v92, v92
	v_exp_f32_e32 v93, v93
	v_pk_add_f32 v[94:95], v[94:95], 1.0 op_sel_hi:[1,0]
	v_pk_add_f32 v[96:97], v[96:97], 1.0 op_sel_hi:[1,0]
	v_pk_add_f32 v[90:91], v[90:91], 1.0 op_sel_hi:[1,0]
	v_pk_add_f32 v[92:93], v[92:93], 1.0 op_sel_hi:[1,0]
	v_rcp_f32_e32 v94, v94
	v_rcp_f32_e32 v95, v95
	v_rcp_f32_e32 v96, v96
	v_rcp_f32_e32 v97, v97
	v_rcp_f32_e32 v90, v90
	v_rcp_f32_e32 v91, v91
	v_rcp_f32_e32 v92, v92
	v_rcp_f32_e32 v93, v93
.LBB0_219:
	v_or_b32_e32 v100, 32, v148
	v_mov_b64_e32 v[98:99], s[8:9]
	v_mad_i64_i32 v[98:99], s[20:21], v100, s85, v[98:99]
	v_cvt_pk_bf16_f32 v94, v94, v95
	v_cvt_pk_bf16_f32 v95, v96, v97
	v_cvt_pk_bf16_f32 v96, v90, v91
	v_lshl_add_u64 v[90:91], v[144:145], 1, v[98:99]
	s_and_b64 vcc, exec, s[6:7]
	v_cvt_pk_bf16_f32 v97, v92, v93
	global_store_dwordx4 v[90:91], v[94:97], off
	s_cbranch_vccnz .LBB0_221
	s_mov_b32 s98, 0xbfb8aa3b
	v_pk_mul_f32 v[86:87], v[86:87], s[98:99] op_sel_hi:[1,0]
	v_pk_mul_f32 v[88:89], v[88:89], s[98:99] op_sel_hi:[1,0]
	v_pk_mul_f32 v[82:83], v[82:83], s[98:99] op_sel_hi:[1,0]
	v_pk_mul_f32 v[84:85], v[84:85], s[98:99] op_sel_hi:[1,0]
	v_exp_f32_e32 v86, v86
	v_exp_f32_e32 v87, v87
	v_exp_f32_e32 v88, v88
	v_exp_f32_e32 v89, v89
	v_exp_f32_e32 v82, v82
	v_exp_f32_e32 v83, v83
	v_exp_f32_e32 v84, v84
	v_exp_f32_e32 v85, v85
	v_pk_add_f32 v[86:87], v[86:87], 1.0 op_sel_hi:[1,0]
	v_pk_add_f32 v[88:89], v[88:89], 1.0 op_sel_hi:[1,0]
	v_pk_add_f32 v[82:83], v[82:83], 1.0 op_sel_hi:[1,0]
	v_pk_add_f32 v[84:85], v[84:85], 1.0 op_sel_hi:[1,0]
	v_rcp_f32_e32 v86, v86
	v_rcp_f32_e32 v87, v87
	v_rcp_f32_e32 v88, v88
	v_rcp_f32_e32 v89, v89
	v_rcp_f32_e32 v82, v82
	v_rcp_f32_e32 v83, v83
	v_rcp_f32_e32 v84, v84
	v_rcp_f32_e32 v85, v85
.LBB0_221:
	s_and_b64 vcc, exec, s[6:7]
	v_cvt_pk_bf16_f32 v86, v86, v87
	v_cvt_pk_bf16_f32 v87, v88, v89
	v_cvt_pk_bf16_f32 v88, v82, v83
	v_cvt_pk_bf16_f32 v89, v84, v85
	global_store_dwordx4 v[90:91], v[86:89], off offset:256
	s_cbranch_vccnz .LBB0_223
	s_mov_b32 s98, 0xbfb8aa3b
	v_pk_mul_f32 v[78:79], v[78:79], s[98:99] op_sel_hi:[1,0]
	v_pk_mul_f32 v[80:81], v[80:81], s[98:99] op_sel_hi:[1,0]
	v_pk_mul_f32 v[74:75], v[74:75], s[98:99] op_sel_hi:[1,0]
	v_pk_mul_f32 v[76:77], v[76:77], s[98:99] op_sel_hi:[1,0]
	v_exp_f32_e32 v78, v78
	v_exp_f32_e32 v79, v79
	v_exp_f32_e32 v80, v80
	v_exp_f32_e32 v81, v81
	v_exp_f32_e32 v74, v74
	v_exp_f32_e32 v75, v75
	v_exp_f32_e32 v76, v76
	v_exp_f32_e32 v77, v77
	v_pk_add_f32 v[78:79], v[78:79], 1.0 op_sel_hi:[1,0]
	v_pk_add_f32 v[80:81], v[80:81], 1.0 op_sel_hi:[1,0]
	v_pk_add_f32 v[74:75], v[74:75], 1.0 op_sel_hi:[1,0]
	v_pk_add_f32 v[76:77], v[76:77], 1.0 op_sel_hi:[1,0]
	v_rcp_f32_e32 v78, v78
	v_rcp_f32_e32 v79, v79
	v_rcp_f32_e32 v80, v80
	v_rcp_f32_e32 v81, v81
	v_rcp_f32_e32 v74, v74
	v_rcp_f32_e32 v75, v75
	v_rcp_f32_e32 v76, v76
	v_rcp_f32_e32 v77, v77
.LBB0_223:
	v_or_b32_e32 v84, 48, v148
	v_mov_b64_e32 v[82:83], s[8:9]
	v_mad_i64_i32 v[82:83], s[20:21], v84, s85, v[82:83]
	v_cvt_pk_bf16_f32 v78, v78, v79
	v_cvt_pk_bf16_f32 v79, v80, v81
	v_cvt_pk_bf16_f32 v80, v74, v75
	v_lshl_add_u64 v[74:75], v[144:145], 1, v[82:83]
	s_and_b64 vcc, exec, s[6:7]
	v_cvt_pk_bf16_f32 v81, v76, v77
	global_store_dwordx4 v[74:75], v[78:81], off
	s_cbranch_vccnz .LBB0_225
	s_mov_b32 s98, 0xbfb8aa3b
	v_pk_mul_f32 v[70:71], v[70:71], s[98:99] op_sel_hi:[1,0]
	v_pk_mul_f32 v[72:73], v[72:73], s[98:99] op_sel_hi:[1,0]
	v_pk_mul_f32 v[66:67], v[66:67], s[98:99] op_sel_hi:[1,0]
	v_pk_mul_f32 v[68:69], v[68:69], s[98:99] op_sel_hi:[1,0]
	v_exp_f32_e32 v70, v70
	v_exp_f32_e32 v71, v71
	v_exp_f32_e32 v72, v72
	v_exp_f32_e32 v73, v73
	v_exp_f32_e32 v66, v66
	v_exp_f32_e32 v67, v67
	v_exp_f32_e32 v68, v68
	v_exp_f32_e32 v69, v69
	v_pk_add_f32 v[70:71], v[70:71], 1.0 op_sel_hi:[1,0]
	v_pk_add_f32 v[72:73], v[72:73], 1.0 op_sel_hi:[1,0]
	v_pk_add_f32 v[66:67], v[66:67], 1.0 op_sel_hi:[1,0]
	v_pk_add_f32 v[68:69], v[68:69], 1.0 op_sel_hi:[1,0]
	v_rcp_f32_e32 v70, v70
	v_rcp_f32_e32 v71, v71
	v_rcp_f32_e32 v72, v72
	v_rcp_f32_e32 v73, v73
	v_rcp_f32_e32 v66, v66
	v_rcp_f32_e32 v67, v67
	v_rcp_f32_e32 v68, v68
	v_rcp_f32_e32 v69, v69
.LBB0_225:
	s_and_b64 vcc, exec, s[6:7]
	v_cvt_pk_bf16_f32 v70, v70, v71
	v_cvt_pk_bf16_f32 v71, v72, v73
	v_cvt_pk_bf16_f32 v72, v66, v67
	v_cvt_pk_bf16_f32 v73, v68, v69
	global_store_dwordx4 v[74:75], v[70:73], off offset:256
	s_cbranch_vccnz .LBB0_227
	s_mov_b32 s98, 0xbfb8aa3b
	v_pk_mul_f32 v[62:63], v[62:63], s[98:99] op_sel_hi:[1,0]
	v_pk_mul_f32 v[64:65], v[64:65], s[98:99] op_sel_hi:[1,0]
	v_pk_mul_f32 v[58:59], v[58:59], s[98:99] op_sel_hi:[1,0]
	v_pk_mul_f32 v[60:61], v[60:61], s[98:99] op_sel_hi:[1,0]
	v_exp_f32_e32 v62, v62
	v_exp_f32_e32 v63, v63
	v_exp_f32_e32 v64, v64
	v_exp_f32_e32 v65, v65
	v_exp_f32_e32 v58, v58
	v_exp_f32_e32 v59, v59
	v_exp_f32_e32 v60, v60
	v_exp_f32_e32 v61, v61
	v_pk_add_f32 v[62:63], v[62:63], 1.0 op_sel_hi:[1,0]
	v_pk_add_f32 v[64:65], v[64:65], 1.0 op_sel_hi:[1,0]
	v_pk_add_f32 v[58:59], v[58:59], 1.0 op_sel_hi:[1,0]
	v_pk_add_f32 v[60:61], v[60:61], 1.0 op_sel_hi:[1,0]
	v_rcp_f32_e32 v62, v62
	v_rcp_f32_e32 v63, v63
	v_rcp_f32_e32 v64, v64
	v_rcp_f32_e32 v65, v65
	v_rcp_f32_e32 v58, v58
	v_rcp_f32_e32 v59, v59
	v_rcp_f32_e32 v60, v60
	v_rcp_f32_e32 v61, v61
.LBB0_227:
	v_add_u32_e32 v68, 0x80, v148
	v_mov_b64_e32 v[66:67], s[8:9]
	v_mad_i64_i32 v[66:67], s[20:21], v68, s85, v[66:67]
	v_cvt_pk_bf16_f32 v62, v62, v63
	v_cvt_pk_bf16_f32 v63, v64, v65
	v_cvt_pk_bf16_f32 v64, v58, v59
	v_lshl_add_u64 v[58:59], v[144:145], 1, v[66:67]
	s_and_b64 vcc, exec, s[6:7]
	v_cvt_pk_bf16_f32 v65, v60, v61
	global_store_dwordx4 v[58:59], v[62:65], off
	s_cbranch_vccnz .LBB0_229
	s_mov_b32 s98, 0xbfb8aa3b
	v_pk_mul_f32 v[54:55], v[54:55], s[98:99] op_sel_hi:[1,0]
	v_pk_mul_f32 v[56:57], v[56:57], s[98:99] op_sel_hi:[1,0]
	v_pk_mul_f32 v[50:51], v[50:51], s[98:99] op_sel_hi:[1,0]
	v_pk_mul_f32 v[52:53], v[52:53], s[98:99] op_sel_hi:[1,0]
	v_exp_f32_e32 v54, v54
	v_exp_f32_e32 v55, v55
	v_exp_f32_e32 v56, v56
	v_exp_f32_e32 v57, v57
	v_exp_f32_e32 v50, v50
	v_exp_f32_e32 v51, v51
	v_exp_f32_e32 v52, v52
	v_exp_f32_e32 v53, v53
	v_pk_add_f32 v[54:55], v[54:55], 1.0 op_sel_hi:[1,0]
	v_pk_add_f32 v[56:57], v[56:57], 1.0 op_sel_hi:[1,0]
	v_pk_add_f32 v[50:51], v[50:51], 1.0 op_sel_hi:[1,0]
	v_pk_add_f32 v[52:53], v[52:53], 1.0 op_sel_hi:[1,0]
	v_rcp_f32_e32 v54, v54
	v_rcp_f32_e32 v55, v55
	v_rcp_f32_e32 v56, v56
	v_rcp_f32_e32 v57, v57
	v_rcp_f32_e32 v50, v50
	v_rcp_f32_e32 v51, v51
	v_rcp_f32_e32 v52, v52
	v_rcp_f32_e32 v53, v53
.LBB0_229:
	s_and_b64 vcc, exec, s[6:7]
	v_cvt_pk_bf16_f32 v54, v54, v55
	v_cvt_pk_bf16_f32 v55, v56, v57
	v_cvt_pk_bf16_f32 v56, v50, v51
	v_cvt_pk_bf16_f32 v57, v52, v53
	global_store_dwordx4 v[58:59], v[54:57], off offset:256
	s_cbranch_vccnz .LBB0_231
	s_mov_b32 s98, 0xbfb8aa3b
	v_pk_mul_f32 v[46:47], v[46:47], s[98:99] op_sel_hi:[1,0]
	v_pk_mul_f32 v[48:49], v[48:49], s[98:99] op_sel_hi:[1,0]
	v_pk_mul_f32 v[42:43], v[42:43], s[98:99] op_sel_hi:[1,0]
	v_pk_mul_f32 v[44:45], v[44:45], s[98:99] op_sel_hi:[1,0]
	v_exp_f32_e32 v46, v46
	v_exp_f32_e32 v47, v47
	v_exp_f32_e32 v48, v48
	v_exp_f32_e32 v49, v49
	v_exp_f32_e32 v42, v42
	v_exp_f32_e32 v43, v43
	v_exp_f32_e32 v44, v44
	v_exp_f32_e32 v45, v45
	v_pk_add_f32 v[46:47], v[46:47], 1.0 op_sel_hi:[1,0]
	v_pk_add_f32 v[48:49], v[48:49], 1.0 op_sel_hi:[1,0]
	v_pk_add_f32 v[42:43], v[42:43], 1.0 op_sel_hi:[1,0]
	v_pk_add_f32 v[44:45], v[44:45], 1.0 op_sel_hi:[1,0]
	v_rcp_f32_e32 v46, v46
	v_rcp_f32_e32 v47, v47
	v_rcp_f32_e32 v48, v48
	v_rcp_f32_e32 v49, v49
	v_rcp_f32_e32 v42, v42
	v_rcp_f32_e32 v43, v43
	v_rcp_f32_e32 v44, v44
	v_rcp_f32_e32 v45, v45
.LBB0_231:
	v_add_u32_e32 v52, 0x90, v148
	v_mov_b64_e32 v[50:51], s[8:9]
	v_mad_i64_i32 v[50:51], s[20:21], v52, s85, v[50:51]
	v_cvt_pk_bf16_f32 v46, v46, v47
	v_cvt_pk_bf16_f32 v47, v48, v49
	v_cvt_pk_bf16_f32 v48, v42, v43
	v_lshl_add_u64 v[42:43], v[144:145], 1, v[50:51]
	s_and_b64 vcc, exec, s[6:7]
	v_cvt_pk_bf16_f32 v49, v44, v45
	global_store_dwordx4 v[42:43], v[46:49], off
	s_cbranch_vccnz .LBB0_233
	s_mov_b32 s98, 0xbfb8aa3b
	v_pk_mul_f32 v[38:39], v[38:39], s[98:99] op_sel_hi:[1,0]
	v_pk_mul_f32 v[40:41], v[40:41], s[98:99] op_sel_hi:[1,0]
	v_pk_mul_f32 v[34:35], v[34:35], s[98:99] op_sel_hi:[1,0]
	v_pk_mul_f32 v[36:37], v[36:37], s[98:99] op_sel_hi:[1,0]
	v_exp_f32_e32 v38, v38
	v_exp_f32_e32 v39, v39
	v_exp_f32_e32 v40, v40
	v_exp_f32_e32 v41, v41
	v_exp_f32_e32 v34, v34
	v_exp_f32_e32 v35, v35
	v_exp_f32_e32 v36, v36
	v_exp_f32_e32 v37, v37
	v_pk_add_f32 v[38:39], v[38:39], 1.0 op_sel_hi:[1,0]
	v_pk_add_f32 v[40:41], v[40:41], 1.0 op_sel_hi:[1,0]
	v_pk_add_f32 v[34:35], v[34:35], 1.0 op_sel_hi:[1,0]
	v_pk_add_f32 v[36:37], v[36:37], 1.0 op_sel_hi:[1,0]
	v_rcp_f32_e32 v38, v38
	v_rcp_f32_e32 v39, v39
	v_rcp_f32_e32 v40, v40
	v_rcp_f32_e32 v41, v41
	v_rcp_f32_e32 v34, v34
	v_rcp_f32_e32 v35, v35
	v_rcp_f32_e32 v36, v36
	v_rcp_f32_e32 v37, v37
.LBB0_233:
	s_and_b64 vcc, exec, s[6:7]
	v_cvt_pk_bf16_f32 v38, v38, v39
	v_cvt_pk_bf16_f32 v39, v40, v41
	v_cvt_pk_bf16_f32 v40, v34, v35
	v_cvt_pk_bf16_f32 v41, v36, v37
	global_store_dwordx4 v[42:43], v[38:41], off offset:256
	s_cbranch_vccnz .LBB0_235
	s_mov_b32 s98, 0xbfb8aa3b
	v_pk_mul_f32 v[22:23], v[22:23], s[98:99] op_sel_hi:[1,0]
	v_pk_mul_f32 v[24:25], v[24:25], s[98:99] op_sel_hi:[1,0]
	v_pk_mul_f32 v[18:19], v[18:19], s[98:99] op_sel_hi:[1,0]
	v_pk_mul_f32 v[20:21], v[20:21], s[98:99] op_sel_hi:[1,0]
	v_exp_f32_e32 v22, v22
	v_exp_f32_e32 v23, v23
	v_exp_f32_e32 v24, v24
	v_exp_f32_e32 v25, v25
	v_exp_f32_e32 v18, v18
	v_exp_f32_e32 v19, v19
	v_exp_f32_e32 v20, v20
	v_exp_f32_e32 v21, v21
	v_pk_add_f32 v[22:23], v[22:23], 1.0 op_sel_hi:[1,0]
	v_pk_add_f32 v[24:25], v[24:25], 1.0 op_sel_hi:[1,0]
	v_pk_add_f32 v[18:19], v[18:19], 1.0 op_sel_hi:[1,0]
	v_pk_add_f32 v[20:21], v[20:21], 1.0 op_sel_hi:[1,0]
	v_rcp_f32_e32 v22, v22
	v_rcp_f32_e32 v23, v23
	v_rcp_f32_e32 v24, v24
	v_rcp_f32_e32 v25, v25
	v_rcp_f32_e32 v18, v18
	v_rcp_f32_e32 v19, v19
	v_rcp_f32_e32 v20, v20
	v_rcp_f32_e32 v21, v21

.LBB0_237:
	s_and_b64 vcc, exec, s[6:7]
	v_cvt_pk_bf16_f32 v20, v26, v27
	v_cvt_pk_bf16_f32 v21, v28, v29
	v_cvt_pk_bf16_f32 v22, v30, v31
	v_cvt_pk_bf16_f32 v23, v32, v33
	global_store_dwordx4 v[18:19], v[20:23], off offset:256
	s_cbranch_vccnz .LBB0_239
	s_mov_b32 s98, 0xbfb8aa3b
	v_pk_mul_f32 v[6:7], v[6:7], s[98:99] op_sel_hi:[1,0]
	v_pk_mul_f32 v[8:9], v[8:9], s[98:99] op_sel_hi:[1,0]
	v_pk_mul_f32 v[2:3], v[2:3], s[98:99] op_sel_hi:[1,0]
	v_pk_mul_f32 v[4:5], v[4:5], s[98:99] op_sel_hi:[1,0]
	v_exp_f32_e32 v6, v6
	v_exp_f32_e32 v7, v7
	v_exp_f32_e32 v8, v8
	v_exp_f32_e32 v9, v9
	v_exp_f32_e32 v2, v2
	v_exp_f32_e32 v3, v3
	v_exp_f32_e32 v4, v4
	v_exp_f32_e32 v5, v5
	v_pk_add_f32 v[6:7], v[6:7], 1.0 op_sel_hi:[1,0]
	v_pk_add_f32 v[8:9], v[8:9], 1.0 op_sel_hi:[1,0]
	v_pk_add_f32 v[2:3], v[2:3], 1.0 op_sel_hi:[1,0]
	v_pk_add_f32 v[4:5], v[4:5], 1.0 op_sel_hi:[1,0]
	v_rcp_f32_e32 v6, v6
	v_rcp_f32_e32 v7, v7
	v_rcp_f32_e32 v8, v8
	v_rcp_f32_e32 v9, v9
	v_rcp_f32_e32 v2, v2
	v_rcp_f32_e32 v3, v3
	v_rcp_f32_e32 v4, v4
	v_rcp_f32_e32 v5, v5

.LBB0_267:
	s_cmp_gt_i32 s4, 9
	v_mbcnt_lo_u32_b32 v144, -1, 0
	v_mbcnt_hi_u32_b32 v144, -1, v144
	s_cselect_b64 s[20:21], -1, 0
	s_cmp_lt_i32 s4, 10
	s_cbranch_scc1 .LBB0_269
	s_mov_b32 s98, 0xbfb8aa3b
	v_pk_mul_f32 v[126:127], v[126:127], s[98:99] op_sel_hi:[1,0]
	v_pk_mul_f32 v[128:129], v[128:129], s[98:99] op_sel_hi:[1,0]
	v_pk_mul_f32 v[122:123], v[122:123], s[98:99] op_sel_hi:[1,0]
	v_pk_mul_f32 v[124:125], v[124:125], s[98:99] op_sel_hi:[1,0]
	v_exp_f32_e32 v126, v126
	v_exp_f32_e32 v127, v127
	v_exp_f32_e32 v128, v128
	v_exp_f32_e32 v129, v129
	v_exp_f32_e32 v122, v122
	v_exp_f32_e32 v123, v123
	v_exp_f32_e32 v124, v124
	v_exp_f32_e32 v125, v125
	v_pk_add_f32 v[126:127], v[126:127], 1.0 op_sel_hi:[1,0]
	v_pk_add_f32 v[128:129], v[128:129], 1.0 op_sel_hi:[1,0]
	v_pk_add_f32 v[122:123], v[122:123], 1.0 op_sel_hi:[1,0]
	v_pk_add_f32 v[124:125], v[124:125], 1.0 op_sel_hi:[1,0]
	v_rcp_f32_e32 v126, v126
	v_rcp_f32_e32 v127, v127
	v_rcp_f32_e32 v128, v128
	v_rcp_f32_e32 v129, v129
	v_rcp_f32_e32 v122, v122
	v_rcp_f32_e32 v123, v123
	v_rcp_f32_e32 v124, v124
	v_rcp_f32_e32 v125, v125
.LBB0_269:
	v_and_or_b32 v145, v144, 15, s39
	v_ashrrev_i32_e32 v144, 1, v144
	s_lshl_b32 s4, s4, 8
	v_and_b32_e32 v149, -8, v144
	v_lshl_add_u32 v148, s43, 8, v145
	v_mov_b64_e32 v[144:145], s[8:9]
	s_or_b32 s4, s4, s34
	v_mad_i64_i32 v[150:151], s[24:25], v148, s85, v[144:145]
	v_add_u32_e32 v144, s4, v149
	v_cvt_pk_bf16_f32 v126, v126, v127
	v_cvt_pk_bf16_f32 v127, v128, v129
	v_cvt_pk_bf16_f32 v129, v124, v125
	v_ashrrev_i32_e32 v145, 31, v144
	v_cndmask_b32_e64 v124, 0, 1, s[20:21]
	v_cvt_pk_bf16_f32 v128, v122, v123
	v_lshl_add_u64 v[122:123], v[144:145], 1, v[150:151]
	v_cmp_ne_u32_e64 s[4:5], 1, v124
	s_andn2_b64 vcc, exec, s[20:21]
	global_store_dwordx4 v[122:123], v[126:129], off
	s_cbranch_vccnz .LBB0_271
	s_mov_b32 s98, 0xbfb8aa3b
	v_pk_mul_f32 v[118:119], v[118:119], s[98:99] op_sel_hi:[1,0]
	v_pk_mul_f32 v[120:121], v[120:121], s[98:99] op_sel_hi:[1,0]
	v_pk_mul_f32 v[114:115], v[114:115], s[98:99] op_sel_hi:[1,0]
	v_pk_mul_f32 v[116:117], v[116:117], s[98:99] op_sel_hi:[1,0]
	v_exp_f32_e32 v118, v118
	v_exp_f32_e32 v119, v119
	v_exp_f32_e32 v120, v120
	v_exp_f32_e32 v121, v121
	v_exp_f32_e32 v114, v114
	v_exp_f32_e32 v115, v115
	v_exp_f32_e32 v116, v116
	v_exp_f32_e32 v117, v117
	v_pk_add_f32 v[118:119], v[118:119], 1.0 op_sel_hi:[1,0]
	v_pk_add_f32 v[120:121], v[120:121], 1.0 op_sel_hi:[1,0]
	v_pk_add_f32 v[114:115], v[114:115], 1.0 op_sel_hi:[1,0]
	v_pk_add_f32 v[116:117], v[116:117], 1.0 op_sel_hi:[1,0]
	v_rcp_f32_e32 v118, v118
	v_rcp_f32_e32 v119, v119
	v_rcp_f32_e32 v120, v120
	v_rcp_f32_e32 v121, v121
	v_rcp_f32_e32 v114, v114
	v_rcp_f32_e32 v115, v115
	v_rcp_f32_e32 v116, v116
	v_rcp_f32_e32 v117, v117
.LBB0_271:
	s_and_b64 vcc, exec, s[4:5]
	v_cvt_pk_bf16_f32 v118, v118, v119
	v_cvt_pk_bf16_f32 v119, v120, v121
	v_cvt_pk_bf16_f32 v120, v114, v115
	v_cvt_pk_bf16_f32 v121, v116, v117
	global_store_dwordx4 v[122:123], v[118:121], off offset:256
	s_cbranch_vccnz .LBB0_273
	s_mov_b32 s98, 0xbfb8aa3b
	v_pk_mul_f32 v[110:111], v[110:111], s[98:99] op_sel_hi:[1,0]
	v_pk_mul_f32 v[112:113], v[112:113], s[98:99] op_sel_hi:[1,0]
	v_pk_mul_f32 v[106:107], v[106:107], s[98:99] op_sel_hi:[1,0]
	v_pk_mul_f32 v[108:109], v[108:109], s[98:99] op_sel_hi:[1,0]
	v_exp_f32_e32 v110, v110
	v_exp_f32_e32 v111, v111
	v_exp_f32_e32 v112, v112
	v_exp_f32_e32 v113, v113
	v_exp_f32_e32 v106, v106
	v_exp_f32_e32 v107, v107
	v_exp_f32_e32 v108, v108
	v_exp_f32_e32 v109, v109
	v_pk_add_f32 v[110:111], v[110:111], 1.0 op_sel_hi:[1,0]
	v_pk_add_f32 v[112:113], v[112:113], 1.0 op_sel_hi:[1,0]
	v_pk_add_f32 v[106:107], v[106:107], 1.0 op_sel_hi:[1,0]
	v_pk_add_f32 v[108:109], v[108:109], 1.0 op_sel_hi:[1,0]
	v_rcp_f32_e32 v110, v110
	v_rcp_f32_e32 v111, v111
	v_rcp_f32_e32 v112, v112
	v_rcp_f32_e32 v113, v113
	v_rcp_f32_e32 v106, v106
	v_rcp_f32_e32 v107, v107
	v_rcp_f32_e32 v108, v108
	v_rcp_f32_e32 v109, v109
.LBB0_273:
	v_or_b32_e32 v116, 16, v148
	v_mov_b64_e32 v[114:115], s[8:9]
	v_mad_i64_i32 v[114:115], s[20:21], v116, s85, v[114:115]
	v_cvt_pk_bf16_f32 v110, v110, v111
	v_cvt_pk_bf16_f32 v111, v112, v113
	v_cvt_pk_bf16_f32 v112, v106, v107
	v_lshl_add_u64 v[106:107], v[144:145], 1, v[114:115]
	s_and_b64 vcc, exec, s[4:5]
	v_cvt_pk_bf16_f32 v113, v108, v109
	global_store_dwordx4 v[106:107], v[110:113], off
	s_cbranch_vccnz .LBB0_275
	s_mov_b32 s98, 0xbfb8aa3b
	v_pk_mul_f32 v[102:103], v[102:103], s[98:99] op_sel_hi:[1,0]
	v_pk_mul_f32 v[104:105], v[104:105], s[98:99] op_sel_hi:[1,0]
	v_pk_mul_f32 v[98:99], v[98:99], s[98:99] op_sel_hi:[1,0]
	v_pk_mul_f32 v[100:101], v[100:101], s[98:99] op_sel_hi:[1,0]
	v_exp_f32_e32 v102, v102
	v_exp_f32_e32 v103, v103
	v_exp_f32_e32 v104, v104
	v_exp_f32_e32 v105, v105
	v_exp_f32_e32 v98, v98
	v_exp_f32_e32 v99, v99
	v_exp_f32_e32 v100, v100
	v_exp_f32_e32 v101, v101
	v_pk_add_f32 v[102:103], v[102:103], 1.0 op_sel_hi:[1,0]
	v_pk_add_f32 v[104:105], v[104:105], 1.0 op_sel_hi:[1,0]
	v_pk_add_f32 v[98:99], v[98:99], 1.0 op_sel_hi:[1,0]
	v_pk_add_f32 v[100:101], v[100:101], 1.0 op_sel_hi:[1,0]
	v_rcp_f32_e32 v102, v102
	v_rcp_f32_e32 v103, v103
	v_rcp_f32_e32 v104, v104
	v_rcp_f32_e32 v105, v105
	v_rcp_f32_e32 v98, v98
	v_rcp_f32_e32 v99, v99
	v_rcp_f32_e32 v100, v100
	v_rcp_f32_e32 v101, v101
.LBB0_275:
	s_and_b64 vcc, exec, s[4:5]
	v_cvt_pk_bf16_f32 v102, v102, v103
	v_cvt_pk_bf16_f32 v103, v104, v105
	v_cvt_pk_bf16_f32 v104, v98, v99
	v_cvt_pk_bf16_f32 v105, v100, v101
	global_store_dwordx4 v[106:107], v[102:105], off offset:256
	s_cbranch_vccnz .LBB0_277
	s_mov_b32 s98, 0xbfb8aa3b
	v_pk_mul_f32 v[94:95], v[94:95], s[98:99] op_sel_hi:[1,0]
	v_pk_mul_f32 v[96:97], v[96:97], s[98:99] op_sel_hi:[1,0]
	v_pk_mul_f32 v[90:91], v[90:91], s[98:99] op_sel_hi:[1,0]
	v_pk_mul_f32 v[92:93], v[92:93], s[98:99] op_sel_hi:[1,0]
	v_exp_f32_e32 v94, v94
	v_exp_f32_e32 v95, v95
	v_exp_f32_e32 v96, v96
	v_exp_f32_e32 v97, v97
	v_exp_f32_e32 v90, v90
	v_exp_f32_e32 v91, v91
	v_exp_f32_e32 v92, v92
	v_exp_f32_e32 v93, v93
	v_pk_add_f32 v[94:95], v[94:95], 1.0 op_sel_hi:[1,0]
	v_pk_add_f32 v[96:97], v[96:97], 1.0 op_sel_hi:[1,0]
	v_pk_add_f32 v[90:91], v[90:91], 1.0 op_sel_hi:[1,0]
	v_pk_add_f32 v[92:93], v[92:93], 1.0 op_sel_hi:[1,0]
	v_rcp_f32_e32 v94, v94
	v_rcp_f32_e32 v95, v95
	v_rcp_f32_e32 v96, v96
	v_rcp_f32_e32 v97, v97
	v_rcp_f32_e32 v90, v90
	v_rcp_f32_e32 v91, v91
	v_rcp_f32_e32 v92, v92
	v_rcp_f32_e32 v93, v93
.LBB0_277:
	v_or_b32_e32 v100, 32, v148
	v_mov_b64_e32 v[98:99], s[8:9]
	v_mad_i64_i32 v[98:99], s[20:21], v100, s85, v[98:99]
	v_cvt_pk_bf16_f32 v94, v94, v95
	v_cvt_pk_bf16_f32 v95, v96, v97
	v_cvt_pk_bf16_f32 v96, v90, v91
	v_lshl_add_u64 v[90:91], v[144:145], 1, v[98:99]
	s_and_b64 vcc, exec, s[4:5]
	v_cvt_pk_bf16_f32 v97, v92, v93
	global_store_dwordx4 v[90:91], v[94:97], off
	s_cbranch_vccnz .LBB0_279
	s_mov_b32 s98, 0xbfb8aa3b
	v_pk_mul_f32 v[86:87], v[86:87], s[98:99] op_sel_hi:[1,0]
	v_pk_mul_f32 v[88:89], v[88:89], s[98:99] op_sel_hi:[1,0]
	v_pk_mul_f32 v[82:83], v[82:83], s[98:99] op_sel_hi:[1,0]
	v_pk_mul_f32 v[84:85], v[84:85], s[98:99] op_sel_hi:[1,0]
	v_exp_f32_e32 v86, v86
	v_exp_f32_e32 v87, v87
	v_exp_f32_e32 v88, v88
	v_exp_f32_e32 v89, v89
	v_exp_f32_e32 v82, v82
	v_exp_f32_e32 v83, v83
	v_exp_f32_e32 v84, v84
	v_exp_f32_e32 v85, v85
	v_pk_add_f32 v[86:87], v[86:87], 1.0 op_sel_hi:[1,0]
	v_pk_add_f32 v[88:89], v[88:89], 1.0 op_sel_hi:[1,0]
	v_pk_add_f32 v[82:83], v[82:83], 1.0 op_sel_hi:[1,0]
	v_pk_add_f32 v[84:85], v[84:85], 1.0 op_sel_hi:[1,0]
	v_rcp_f32_e32 v86, v86
	v_rcp_f32_e32 v87, v87
	v_rcp_f32_e32 v88, v88
	v_rcp_f32_e32 v89, v89
	v_rcp_f32_e32 v82, v82
	v_rcp_f32_e32 v83, v83
	v_rcp_f32_e32 v84, v84
	v_rcp_f32_e32 v85, v85
.LBB0_279:
	s_and_b64 vcc, exec, s[4:5]
	v_cvt_pk_bf16_f32 v86, v86, v87
	v_cvt_pk_bf16_f32 v87, v88, v89
	v_cvt_pk_bf16_f32 v88, v82, v83
	v_cvt_pk_bf16_f32 v89, v84, v85
	global_store_dwordx4 v[90:91], v[86:89], off offset:256
	s_cbranch_vccnz .LBB0_281
	s_mov_b32 s98, 0xbfb8aa3b
	v_pk_mul_f32 v[78:79], v[78:79], s[98:99] op_sel_hi:[1,0]
	v_pk_mul_f32 v[80:81], v[80:81], s[98:99] op_sel_hi:[1,0]
	v_pk_mul_f32 v[74:75], v[74:75], s[98:99] op_sel_hi:[1,0]
	v_pk_mul_f32 v[76:77], v[76:77], s[98:99] op_sel_hi:[1,0]
	v_exp_f32_e32 v78, v78
	v_exp_f32_e32 v79, v79
	v_exp_f32_e32 v80, v80
	v_exp_f32_e32 v81, v81
	v_exp_f32_e32 v74, v74
	v_exp_f32_e32 v75, v75
	v_exp_f32_e32 v76, v76
	v_exp_f32_e32 v77, v77
	v_pk_add_f32 v[78:79], v[78:79], 1.0 op_sel_hi:[1,0]
	v_pk_add_f32 v[80:81], v[80:81], 1.0 op_sel_hi:[1,0]
	v_pk_add_f32 v[74:75], v[74:75], 1.0 op_sel_hi:[1,0]
	v_pk_add_f32 v[76:77], v[76:77], 1.0 op_sel_hi:[1,0]
	v_rcp_f32_e32 v78, v78
	v_rcp_f32_e32 v79, v79
	v_rcp_f32_e32 v80, v80
	v_rcp_f32_e32 v81, v81
	v_rcp_f32_e32 v74, v74
	v_rcp_f32_e32 v75, v75
	v_rcp_f32_e32 v76, v76
	v_rcp_f32_e32 v77, v77
.LBB0_281:
	v_or_b32_e32 v84, 48, v148
	v_mov_b64_e32 v[82:83], s[8:9]
	v_mad_i64_i32 v[82:83], s[20:21], v84, s85, v[82:83]
	v_cvt_pk_bf16_f32 v78, v78, v79
	v_cvt_pk_bf16_f32 v79, v80, v81
	v_cvt_pk_bf16_f32 v80, v74, v75
	v_lshl_add_u64 v[74:75], v[144:145], 1, v[82:83]
	s_and_b64 vcc, exec, s[4:5]
	v_cvt_pk_bf16_f32 v81, v76, v77
	global_store_dwordx4 v[74:75], v[78:81], off
	s_cbranch_vccnz .LBB0_283
	s_mov_b32 s98, 0xbfb8aa3b
	v_pk_mul_f32 v[70:71], v[70:71], s[98:99] op_sel_hi:[1,0]
	v_pk_mul_f32 v[72:73], v[72:73], s[98:99] op_sel_hi:[1,0]
	v_pk_mul_f32 v[66:67], v[66:67], s[98:99] op_sel_hi:[1,0]
	v_pk_mul_f32 v[68:69], v[68:69], s[98:99] op_sel_hi:[1,0]
	v_exp_f32_e32 v70, v70
	v_exp_f32_e32 v71, v71
	v_exp_f32_e32 v72, v72
	v_exp_f32_e32 v73, v73
	v_exp_f32_e32 v66, v66
	v_exp_f32_e32 v67, v67
	v_exp_f32_e32 v68, v68
	v_exp_f32_e32 v69, v69
	v_pk_add_f32 v[70:71], v[70:71], 1.0 op_sel_hi:[1,0]
	v_pk_add_f32 v[72:73], v[72:73], 1.0 op_sel_hi:[1,0]
	v_pk_add_f32 v[66:67], v[66:67], 1.0 op_sel_hi:[1,0]
	v_pk_add_f32 v[68:69], v[68:69], 1.0 op_sel_hi:[1,0]
	v_rcp_f32_e32 v70, v70
	v_rcp_f32_e32 v71, v71
	v_rcp_f32_e32 v72, v72
	v_rcp_f32_e32 v73, v73
	v_rcp_f32_e32 v66, v66
	v_rcp_f32_e32 v67, v67
	v_rcp_f32_e32 v68, v68
	v_rcp_f32_e32 v69, v69
.LBB0_283:
	s_and_b64 vcc, exec, s[4:5]
	v_cvt_pk_bf16_f32 v70, v70, v71
	v_cvt_pk_bf16_f32 v71, v72, v73
	v_cvt_pk_bf16_f32 v72, v66, v67
	v_cvt_pk_bf16_f32 v73, v68, v69
	global_store_dwordx4 v[74:75], v[70:73], off offset:256
	s_cbranch_vccnz .LBB0_285
	s_mov_b32 s98, 0xbfb8aa3b
	v_pk_mul_f32 v[62:63], v[62:63], s[98:99] op_sel_hi:[1,0]
	v_pk_mul_f32 v[64:65], v[64:65], s[98:99] op_sel_hi:[1,0]
	v_pk_mul_f32 v[58:59], v[58:59], s[98:99] op_sel_hi:[1,0]
	v_pk_mul_f32 v[60:61], v[60:61], s[98:99] op_sel_hi:[1,0]
	v_exp_f32_e32 v62, v62
	v_exp_f32_e32 v63, v63
	v_exp_f32_e32 v64, v64
	v_exp_f32_e32 v65, v65
	v_exp_f32_e32 v58, v58
	v_exp_f32_e32 v59, v59
	v_exp_f32_e32 v60, v60
	v_exp_f32_e32 v61, v61
	v_pk_add_f32 v[62:63], v[62:63], 1.0 op_sel_hi:[1,0]
	v_pk_add_f32 v[64:65], v[64:65], 1.0 op_sel_hi:[1,0]
	v_pk_add_f32 v[58:59], v[58:59], 1.0 op_sel_hi:[1,0]
	v_pk_add_f32 v[60:61], v[60:61], 1.0 op_sel_hi:[1,0]
	v_rcp_f32_e32 v62, v62
	v_rcp_f32_e32 v63, v63
	v_rcp_f32_e32 v64, v64
	v_rcp_f32_e32 v65, v65
	v_rcp_f32_e32 v58, v58
	v_rcp_f32_e32 v59, v59
	v_rcp_f32_e32 v60, v60
	v_rcp_f32_e32 v61, v61
.LBB0_285:
	v_add_u32_e32 v68, 0x80, v148
	v_mov_b64_e32 v[66:67], s[8:9]
	v_mad_i64_i32 v[66:67], s[20:21], v68, s85, v[66:67]
	v_cvt_pk_bf16_f32 v62, v62, v63
	v_cvt_pk_bf16_f32 v63, v64, v65
	v_cvt_pk_bf16_f32 v64, v58, v59
	v_lshl_add_u64 v[58:59], v[144:145], 1, v[66:67]
	s_and_b64 vcc, exec, s[4:5]
	v_cvt_pk_bf16_f32 v65, v60, v61
	global_store_dwordx4 v[58:59], v[62:65], off
	s_cbranch_vccnz .LBB0_287
	s_mov_b32 s98, 0xbfb8aa3b
	v_pk_mul_f32 v[54:55], v[54:55], s[98:99] op_sel_hi:[1,0]
	v_pk_mul_f32 v[56:57], v[56:57], s[98:99] op_sel_hi:[1,0]
	v_pk_mul_f32 v[50:51], v[50:51], s[98:99] op_sel_hi:[1,0]
	v_pk_mul_f32 v[52:53], v[52:53], s[98:99] op_sel_hi:[1,0]
	v_exp_f32_e32 v54, v54
	v_exp_f32_e32 v55, v55
	v_exp_f32_e32 v56, v56
	v_exp_f32_e32 v57, v57
	v_exp_f32_e32 v50, v50
	v_exp_f32_e32 v51, v51
	v_exp_f32_e32 v52, v52
	v_exp_f32_e32 v53, v53
	v_pk_add_f32 v[54:55], v[54:55], 1.0 op_sel_hi:[1,0]
	v_pk_add_f32 v[56:57], v[56:57], 1.0 op_sel_hi:[1,0]
	v_pk_add_f32 v[50:51], v[50:51], 1.0 op_sel_hi:[1,0]
	v_pk_add_f32 v[52:53], v[52:53], 1.0 op_sel_hi:[1,0]
	v_rcp_f32_e32 v54, v54
	v_rcp_f32_e32 v55, v55
	v_rcp_f32_e32 v56, v56
	v_rcp_f32_e32 v57, v57
	v_rcp_f32_e32 v50, v50
	v_rcp_f32_e32 v51, v51
	v_rcp_f32_e32 v52, v52
	v_rcp_f32_e32 v53, v53
.LBB0_287:
	s_and_b64 vcc, exec, s[4:5]
	v_cvt_pk_bf16_f32 v54, v54, v55
	v_cvt_pk_bf16_f32 v55, v56, v57
	v_cvt_pk_bf16_f32 v56, v50, v51
	v_cvt_pk_bf16_f32 v57, v52, v53
	global_store_dwordx4 v[58:59], v[54:57], off offset:256
	s_cbranch_vccnz .LBB0_289
	s_mov_b32 s98, 0xbfb8aa3b
	v_pk_mul_f32 v[46:47], v[46:47], s[98:99] op_sel_hi:[1,0]
	v_pk_mul_f32 v[48:49], v[48:49], s[98:99] op_sel_hi:[1,0]
	v_pk_mul_f32 v[42:43], v[42:43], s[98:99] op_sel_hi:[1,0]
	v_pk_mul_f32 v[44:45], v[44:45], s[98:99] op_sel_hi:[1,0]
	v_exp_f32_e32 v46, v46
	v_exp_f32_e32 v47, v47
	v_exp_f32_e32 v48, v48
	v_exp_f32_e32 v49, v49
	v_exp_f32_e32 v42, v42
	v_exp_f32_e32 v43, v43
	v_exp_f32_e32 v44, v44
	v_exp_f32_e32 v45, v45
	v_pk_add_f32 v[46:47], v[46:47], 1.0 op_sel_hi:[1,0]
	v_pk_add_f32 v[48:49], v[48:49], 1.0 op_sel_hi:[1,0]
	v_pk_add_f32 v[42:43], v[42:43], 1.0 op_sel_hi:[1,0]
	v_pk_add_f32 v[44:45], v[44:45], 1.0 op_sel_hi:[1,0]
	v_rcp_f32_e32 v46, v46
	v_rcp_f32_e32 v47, v47
	v_rcp_f32_e32 v48, v48
	v_rcp_f32_e32 v49, v49
	v_rcp_f32_e32 v42, v42
	v_rcp_f32_e32 v43, v43
	v_rcp_f32_e32 v44, v44
	v_rcp_f32_e32 v45, v45
.LBB0_289:
	v_add_u32_e32 v52, 0x90, v148
	v_mov_b64_e32 v[50:51], s[8:9]
	v_mad_i64_i32 v[50:51], s[20:21], v52, s85, v[50:51]
	v_cvt_pk_bf16_f32 v46, v46, v47
	v_cvt_pk_bf16_f32 v47, v48, v49
	v_cvt_pk_bf16_f32 v48, v42, v43
	v_lshl_add_u64 v[42:43], v[144:145], 1, v[50:51]
	s_and_b64 vcc, exec, s[4:5]
	v_cvt_pk_bf16_f32 v49, v44, v45
	global_store_dwordx4 v[42:43], v[46:49], off
	s_cbranch_vccnz .LBB0_291
	s_mov_b32 s98, 0xbfb8aa3b
	v_pk_mul_f32 v[38:39], v[38:39], s[98:99] op_sel_hi:[1,0]
	v_pk_mul_f32 v[40:41], v[40:41], s[98:99] op_sel_hi:[1,0]
	v_pk_mul_f32 v[34:35], v[34:35], s[98:99] op_sel_hi:[1,0]
	v_pk_mul_f32 v[36:37], v[36:37], s[98:99] op_sel_hi:[1,0]
	v_exp_f32_e32 v38, v38
	v_exp_f32_e32 v39, v39
	v_exp_f32_e32 v40, v40
	v_exp_f32_e32 v41, v41
	v_exp_f32_e32 v34, v34
	v_exp_f32_e32 v35, v35
	v_exp_f32_e32 v36, v36
	v_exp_f32_e32 v37, v37
	v_pk_add_f32 v[38:39], v[38:39], 1.0 op_sel_hi:[1,0]
	v_pk_add_f32 v[40:41], v[40:41], 1.0 op_sel_hi:[1,0]
	v_pk_add_f32 v[34:35], v[34:35], 1.0 op_sel_hi:[1,0]
	v_pk_add_f32 v[36:37], v[36:37], 1.0 op_sel_hi:[1,0]
	v_rcp_f32_e32 v38, v38
	v_rcp_f32_e32 v39, v39
	v_rcp_f32_e32 v40, v40
	v_rcp_f32_e32 v41, v41
	v_rcp_f32_e32 v34, v34
	v_rcp_f32_e32 v35, v35
	v_rcp_f32_e32 v36, v36
	v_rcp_f32_e32 v37, v37
.LBB0_291:
	s_and_b64 vcc, exec, s[4:5]
	v_cvt_pk_bf16_f32 v38, v38, v39
	v_cvt_pk_bf16_f32 v39, v40, v41
	v_cvt_pk_bf16_f32 v40, v34, v35
	v_cvt_pk_bf16_f32 v41, v36, v37
	global_store_dwordx4 v[42:43], v[38:41], off offset:256
	s_cbranch_vccnz .LBB0_293
	s_mov_b32 s98, 0xbfb8aa3b
	v_pk_mul_f32 v[22:23], v[22:23], s[98:99] op_sel_hi:[1,0]
	v_pk_mul_f32 v[24:25], v[24:25], s[98:99] op_sel_hi:[1,0]
	v_pk_mul_f32 v[18:19], v[18:19], s[98:99] op_sel_hi:[1,0]
	v_pk_mul_f32 v[20:21], v[20:21], s[98:99] op_sel_hi:[1,0]
	v_exp_f32_e32 v22, v22
	v_exp_f32_e32 v23, v23
	v_exp_f32_e32 v24, v24
	v_exp_f32_e32 v25, v25
	v_exp_f32_e32 v18, v18
	v_exp_f32_e32 v19, v19
	v_exp_f32_e32 v20, v20
	v_exp_f32_e32 v21, v21
	v_pk_add_f32 v[22:23], v[22:23], 1.0 op_sel_hi:[1,0]
	v_pk_add_f32 v[24:25], v[24:25], 1.0 op_sel_hi:[1,0]
	v_pk_add_f32 v[18:19], v[18:19], 1.0 op_sel_hi:[1,0]
	v_pk_add_f32 v[20:21], v[20:21], 1.0 op_sel_hi:[1,0]
	v_rcp_f32_e32 v22, v22
	v_rcp_f32_e32 v23, v23
	v_rcp_f32_e32 v24, v24
	v_rcp_f32_e32 v25, v25
	v_rcp_f32_e32 v18, v18
	v_rcp_f32_e32 v19, v19
	v_rcp_f32_e32 v20, v20
	v_rcp_f32_e32 v21, v21

.LBB0_295:
	s_and_b64 vcc, exec, s[4:5]
	v_cvt_pk_bf16_f32 v20, v26, v27
	v_cvt_pk_bf16_f32 v21, v28, v29
	v_cvt_pk_bf16_f32 v22, v30, v31
	v_cvt_pk_bf16_f32 v23, v32, v33
	global_store_dwordx4 v[18:19], v[20:23], off offset:256
	s_cbranch_vccnz .LBB0_297
	s_mov_b32 s98, 0xbfb8aa3b
	v_pk_mul_f32 v[6:7], v[6:7], s[98:99] op_sel_hi:[1,0]
	v_pk_mul_f32 v[8:9], v[8:9], s[98:99] op_sel_hi:[1,0]
	v_pk_mul_f32 v[2:3], v[2:3], s[98:99] op_sel_hi:[1,0]
	v_pk_mul_f32 v[4:5], v[4:5], s[98:99] op_sel_hi:[1,0]
	v_exp_f32_e32 v6, v6
	v_exp_f32_e32 v7, v7
	v_exp_f32_e32 v8, v8
	v_exp_f32_e32 v9, v9
	v_exp_f32_e32 v2, v2
	v_exp_f32_e32 v3, v3
	v_exp_f32_e32 v4, v4
	v_exp_f32_e32 v5, v5
	v_pk_add_f32 v[6:7], v[6:7], 1.0 op_sel_hi:[1,0]
	v_pk_add_f32 v[8:9], v[8:9], 1.0 op_sel_hi:[1,0]
	v_pk_add_f32 v[2:3], v[2:3], 1.0 op_sel_hi:[1,0]
	v_pk_add_f32 v[4:5], v[4:5], 1.0 op_sel_hi:[1,0]
	v_rcp_f32_e32 v6, v6
	v_rcp_f32_e32 v7, v7
	v_rcp_f32_e32 v8, v8
	v_rcp_f32_e32 v9, v9
	v_rcp_f32_e32 v2, v2
	v_rcp_f32_e32 v3, v3
	v_rcp_f32_e32 v4, v4
	v_rcp_f32_e32 v5, v5

.LBB0_1080:
	s_lshl_b32 s34, s7, 10
	s_ashr_i32 s35, s34, 31
	s_add_i32 s21, s34, 0x400
	v_mbcnt_lo_u32_b32 v144, -1, 0
	v_mbcnt_hi_u32_b32 v144, -1, v144
	s_cmp_eq_u32 s7, 2
	s_cselect_b64 s[30:31], -1, 0
	s_and_b64 s[36:37], s[30:31], exec
	v_and_or_b32 v145, v144, 15, s33
	v_ashrrev_i32_e32 v144, 1, v144
	s_cselect_b32 s36, 0x800, s21
	s_lshl_b32 s6, s6, 8
	v_and_b32_e32 v147, -8, v144
	v_lshl_add_u32 v146, s64, 8, v145
	v_mov_b64_e32 v[144:145], s[8:9]
	s_or_b32 s6, s6, s40
	v_mad_i64_i32 v[144:145], s[38:39], v146, s85, v[144:145]
	v_lshl_add_u64 v[150:151], v[144:145], 0, s[88:89]
	v_add_u32_e32 v144, s6, v147
	v_ashrrev_i32_e32 v145, 31, v144
	s_ashr_i32 s37, s36, 31
	v_lshl_add_u64 v[152:153], s[34:35], 1, v[150:151]
	v_lshlrev_b64 v[148:149], 1, v[144:145]
	v_lshl_add_u64 v[150:151], s[36:37], 1, v[150:151]
	v_lshl_add_u64 v[152:153], v[152:153], 0, v[148:149]
	v_lshl_add_u64 v[154:155], v[150:151], 0, v[148:149]
	global_load_dwordx4 v[158:161], v[152:153], off
	global_load_dwordx4 v[162:165], v[154:155], off
	global_load_dwordx4 v[176:179], v[152:153], off offset:256
	global_load_dwordx4 v[180:183], v[154:155], off offset:256
	v_ashrrev_i32_e32 v147, 31, v146
	v_lshlrev_b64 v[150:151], 11, v[146:147]
	v_lshl_add_u64 v[150:151], s[10:11], 0, v[150:151]
	s_cmp_lg_u32 s7, 2
	s_waitcnt vmcnt(2)
	v_lshlrev_b32_e32 v147, 16, v158
	v_and_b32_e32 v166, 0xffff0000, v158
	v_lshlrev_b32_e32 v167, 16, v159
	v_and_b32_e32 v168, 0xffff0000, v159
	v_lshlrev_b32_e32 v158, 16, v162
	v_and_b32_e32 v159, 0xffff0000, v162
	v_lshlrev_b32_e32 v162, 16, v163
	v_and_b32_e32 v163, 0xffff0000, v163
	v_lshlrev_b32_e32 v169, 16, v160
	v_and_b32_e32 v170, 0xffff0000, v160
	v_lshlrev_b32_e32 v171, 16, v161
	v_and_b32_e32 v172, 0xffff0000, v161
	v_lshlrev_b32_e32 v160, 16, v164
	v_and_b32_e32 v161, 0xffff0000, v164
	v_lshlrev_b32_e32 v164, 16, v165
	v_and_b32_e32 v165, 0xffff0000, v165
	v_max_f32_e32 v158, 0x1e3ce508, v158
	v_max_f32_e32 v159, 0x1e3ce508, v159
	v_max_f32_e32 v162, 0x1e3ce508, v162
	v_max_f32_e32 v163, 0x1e3ce508, v163
	v_max_f32_e32 v160, 0x1e3ce508, v160
	v_max_f32_e32 v161, 0x1e3ce508, v161
	v_max_f32_e32 v164, 0x1e3ce508, v164
	v_max_f32_e32 v165, 0x1e3ce508, v165
	v_rcp_f32_e32 v158, v158
	v_rcp_f32_e32 v159, v159
	v_rcp_f32_e32 v162, v162
	v_rcp_f32_e32 v163, v163
	v_rcp_f32_e32 v160, v160
	v_rcp_f32_e32 v161, v161
	v_rcp_f32_e32 v164, v164
	v_rcp_f32_e32 v165, v165
	v_cndmask_b32_e64 v158, v158, 1.0, s[30:31]
	v_cndmask_b32_e64 v159, v159, 1.0, s[30:31]
	v_cndmask_b32_e64 v162, v162, 1.0, s[30:31]
	v_cndmask_b32_e64 v163, v163, 1.0, s[30:31]
	v_cndmask_b32_e64 v173, v160, 1.0, s[30:31]
	v_cndmask_b32_e64 v174, v161, 1.0, s[30:31]
	v_cndmask_b32_e64 v164, v164, 1.0, s[30:31]
	v_cndmask_b32_e64 v165, v165, 1.0, s[30:31]
	v_mul_f32_e32 v158, v158, v147
	v_mul_f32_e32 v159, v159, v166
	v_mul_f32_e32 v160, v162, v167
	v_mul_f32_e32 v161, v163, v168
	v_mul_f32_e32 v162, v173, v169
	v_mul_f32_e32 v163, v174, v170
	v_mul_f32_e32 v164, v164, v171
	v_mul_f32_e32 v165, v165, v172
	v_pk_mul_f32 v[112:113], v[112:113], v[160:161]
	v_pk_mul_f32 v[110:111], v[110:111], v[158:159]
	v_pk_mul_f32 v[108:109], v[108:109], v[164:165]
	v_pk_mul_f32 v[106:107], v[106:107], v[162:163]
	s_waitcnt vmcnt(0)
	s_cbranch_scc1 .LBB0_1082
	v_lshl_add_u64 v[162:163], v[144:145], 1, v[150:151]
	v_cvt_pk_bf16_f32 v158, v110, v111
	v_cvt_pk_bf16_f32 v159, v112, v113
	v_cvt_pk_bf16_f32 v160, v106, v107
	v_cvt_pk_bf16_f32 v161, v108, v109
	global_store_dwordx4 v[162:163], v[158:161], off
.LBB0_1082:
	v_cndmask_b32_e64 v147, 0, 1, s[30:31]
	v_cmp_ne_u32_e64 s[6:7], 1, v147
	s_andn2_b64 vcc, exec, s[30:31]
	v_lshlrev_b32_e32 v147, 16, v176
	v_lshlrev_b32_e32 v163, 16, v180
	v_and_b32_e32 v180, 0xffff0000, v180
	v_lshlrev_b32_e32 v164, 16, v181
	v_and_b32_e32 v181, 0xffff0000, v181
	v_lshlrev_b32_e32 v167, 16, v182
	v_and_b32_e32 v182, 0xffff0000, v182
	v_lshlrev_b32_e32 v168, 16, v183
	v_and_b32_e32 v183, 0xffff0000, v183
	v_max_f32_e32 v163, 0x1e3ce508, v163
	v_max_f32_e32 v180, 0x1e3ce508, v180
	v_max_f32_e32 v164, 0x1e3ce508, v164
	v_max_f32_e32 v181, 0x1e3ce508, v181
	v_max_f32_e32 v167, 0x1e3ce508, v167
	v_max_f32_e32 v182, 0x1e3ce508, v182
	v_max_f32_e32 v168, 0x1e3ce508, v168
	v_max_f32_e32 v183, 0x1e3ce508, v183
	v_rcp_f32_e32 v163, v163
	v_rcp_f32_e32 v180, v180
	v_rcp_f32_e32 v164, v164
	v_rcp_f32_e32 v181, v181
	v_rcp_f32_e32 v167, v167
	v_rcp_f32_e32 v182, v182
	v_rcp_f32_e32 v168, v168
	v_rcp_f32_e32 v183, v183
	v_and_b32_e32 v176, 0xffff0000, v176
	v_lshlrev_b32_e32 v162, 16, v177
	v_and_b32_e32 v177, 0xffff0000, v177
	v_lshlrev_b32_e32 v165, 16, v178
	v_and_b32_e32 v178, 0xffff0000, v178
	v_lshlrev_b32_e32 v166, 16, v179
	v_and_b32_e32 v179, 0xffff0000, v179
	v_cndmask_b32_e64 v163, v163, 1.0, s[30:31]
	v_cndmask_b32_e64 v169, v180, 1.0, s[30:31]
	v_cndmask_b32_e64 v164, v164, 1.0, s[30:31]
	v_cndmask_b32_e64 v170, v181, 1.0, s[30:31]
	v_cndmask_b32_e64 v167, v167, 1.0, s[30:31]
	v_cndmask_b32_e64 v171, v182, 1.0, s[30:31]
	v_cndmask_b32_e64 v168, v168, 1.0, s[30:31]
	v_cndmask_b32_e64 v172, v183, 1.0, s[30:31]
	v_mul_f32_e32 v180, v163, v147
	v_mul_f32_e32 v181, v169, v176
	v_mul_f32_e32 v182, v164, v162
	v_mul_f32_e32 v183, v170, v177
	v_mul_f32_e32 v176, v167, v165
	v_mul_f32_e32 v177, v171, v178
	v_mul_f32_e32 v178, v168, v166
	v_mul_f32_e32 v179, v172, v179
	v_pk_mul_f32 v[80:81], v[80:81], v[182:183]
	v_pk_mul_f32 v[78:79], v[78:79], v[180:181]
	v_pk_mul_f32 v[76:77], v[76:77], v[178:179]
	v_pk_mul_f32 v[74:75], v[74:75], v[176:177]
	s_cbranch_vccnz .LBB0_1084
	v_lshl_add_u64 v[150:151], v[144:145], 1, v[150:151]
	v_cvt_pk_bf16_f32 v180, v78, v79
	v_cvt_pk_bf16_f32 v181, v80, v81
	v_cvt_pk_bf16_f32 v182, v74, v75
	v_cvt_pk_bf16_f32 v183, v76, v77
	global_store_dwordx4 v[150:151], v[180:183], off offset:256
.LBB0_1084:
	v_or_b32_e32 v150, 16, v146
	s_nop 0
	v_mov_b64_e32 v[152:153], s[8:9]
	v_mad_i64_i32 v[152:153], s[38:39], v150, s85, v[152:153]
	v_lshl_add_u64 v[154:155], v[152:153], 0, s[88:89]
	v_lshl_add_u64 v[152:153], s[34:35], 1, v[154:155]
	v_lshl_add_u64 v[154:155], s[36:37], 1, v[154:155]
	v_lshl_add_u64 v[152:153], v[152:153], 0, v[148:149]
	v_lshl_add_u64 v[154:155], v[154:155], 0, v[148:149]
	global_load_dwordx4 v[158:161], v[152:153], off
	global_load_dwordx4 v[162:165], v[154:155], off
	global_load_dwordx4 v[176:179], v[152:153], off offset:256
	global_load_dwordx4 v[180:183], v[154:155], off offset:256
	v_ashrrev_i32_e32 v151, 31, v150
	v_lshlrev_b64 v[150:151], 11, v[150:151]
	s_and_b64 vcc, exec, s[6:7]
	v_lshl_add_u64 v[150:151], s[10:11], 0, v[150:151]
	s_waitcnt vmcnt(3)
	v_lshlrev_b32_e32 v147, 16, v158
	v_and_b32_e32 v166, 0xffff0000, v158
	v_lshlrev_b32_e32 v167, 16, v159
	v_and_b32_e32 v168, 0xffff0000, v159
	s_waitcnt vmcnt(2)
	v_lshlrev_b32_e32 v158, 16, v162
	v_and_b32_e32 v159, 0xffff0000, v162
	v_lshlrev_b32_e32 v162, 16, v163
	v_and_b32_e32 v163, 0xffff0000, v163
	v_lshlrev_b32_e32 v169, 16, v160
	v_and_b32_e32 v170, 0xffff0000, v160
	v_lshlrev_b32_e32 v171, 16, v161
	v_and_b32_e32 v172, 0xffff0000, v161
	v_lshlrev_b32_e32 v160, 16, v164
	v_and_b32_e32 v161, 0xffff0000, v164
	v_lshlrev_b32_e32 v164, 16, v165
	v_and_b32_e32 v165, 0xffff0000, v165
	v_max_f32_e32 v158, 0x1e3ce508, v158
	v_max_f32_e32 v159, 0x1e3ce508, v159
	v_max_f32_e32 v162, 0x1e3ce508, v162
	v_max_f32_e32 v163, 0x1e3ce508, v163
	v_max_f32_e32 v160, 0x1e3ce508, v160
	v_max_f32_e32 v161, 0x1e3ce508, v161
	v_max_f32_e32 v164, 0x1e3ce508, v164
	v_max_f32_e32 v165, 0x1e3ce508, v165
	v_rcp_f32_e32 v158, v158
	v_rcp_f32_e32 v159, v159
	v_rcp_f32_e32 v162, v162
	v_rcp_f32_e32 v163, v163
	v_rcp_f32_e32 v160, v160
	v_rcp_f32_e32 v161, v161
	v_rcp_f32_e32 v164, v164
	v_rcp_f32_e32 v165, v165
	v_cndmask_b32_e64 v158, v158, 1.0, s[30:31]
	v_cndmask_b32_e64 v159, v159, 1.0, s[30:31]
	v_cndmask_b32_e64 v162, v162, 1.0, s[30:31]
	v_cndmask_b32_e64 v163, v163, 1.0, s[30:31]
	v_cndmask_b32_e64 v173, v160, 1.0, s[30:31]
	v_cndmask_b32_e64 v174, v161, 1.0, s[30:31]
	v_cndmask_b32_e64 v164, v164, 1.0, s[30:31]
	v_cndmask_b32_e64 v165, v165, 1.0, s[30:31]
	v_mul_f32_e32 v158, v158, v147
	v_mul_f32_e32 v159, v159, v166
	v_mul_f32_e32 v160, v162, v167
	v_mul_f32_e32 v161, v163, v168
	v_mul_f32_e32 v162, v173, v169
	v_mul_f32_e32 v163, v174, v170
	v_mul_f32_e32 v164, v164, v171
	v_mul_f32_e32 v165, v165, v172
	v_pk_mul_f32 v[104:105], v[104:105], v[160:161]
	v_pk_mul_f32 v[102:103], v[102:103], v[158:159]
	v_pk_mul_f32 v[100:101], v[100:101], v[164:165]
	v_pk_mul_f32 v[98:99], v[98:99], v[162:163]
	s_waitcnt vmcnt(0)
	s_cbranch_vccnz .LBB0_1086
	v_lshl_add_u64 v[162:163], v[144:145], 1, v[150:151]
	v_cvt_pk_bf16_f32 v158, v102, v103
	v_cvt_pk_bf16_f32 v159, v104, v105
	v_cvt_pk_bf16_f32 v160, v98, v99
	v_cvt_pk_bf16_f32 v161, v100, v101
	global_store_dwordx4 v[162:163], v[158:161], off
.LBB0_1086:
	s_and_b64 vcc, exec, s[6:7]
	v_lshlrev_b32_e32 v147, 16, v176
	v_lshlrev_b32_e32 v163, 16, v180
	v_and_b32_e32 v180, 0xffff0000, v180
	v_lshlrev_b32_e32 v164, 16, v181
	v_and_b32_e32 v181, 0xffff0000, v181
	v_lshlrev_b32_e32 v167, 16, v182
	v_and_b32_e32 v182, 0xffff0000, v182
	v_lshlrev_b32_e32 v168, 16, v183
	v_and_b32_e32 v183, 0xffff0000, v183
	v_max_f32_e32 v163, 0x1e3ce508, v163
	v_max_f32_e32 v180, 0x1e3ce508, v180
	v_max_f32_e32 v164, 0x1e3ce508, v164
	v_max_f32_e32 v181, 0x1e3ce508, v181
	v_max_f32_e32 v167, 0x1e3ce508, v167
	v_max_f32_e32 v182, 0x1e3ce508, v182
	v_max_f32_e32 v168, 0x1e3ce508, v168
	v_max_f32_e32 v183, 0x1e3ce508, v183
	v_rcp_f32_e32 v163, v163
	v_rcp_f32_e32 v180, v180
	v_rcp_f32_e32 v164, v164
	v_rcp_f32_e32 v181, v181
	v_rcp_f32_e32 v167, v167
	v_rcp_f32_e32 v182, v182
	v_rcp_f32_e32 v168, v168
	v_rcp_f32_e32 v183, v183
	v_and_b32_e32 v176, 0xffff0000, v176
	v_lshlrev_b32_e32 v162, 16, v177
	v_and_b32_e32 v177, 0xffff0000, v177
	v_lshlrev_b32_e32 v165, 16, v178
	v_and_b32_e32 v178, 0xffff0000, v178
	v_lshlrev_b32_e32 v166, 16, v179
	v_and_b32_e32 v179, 0xffff0000, v179
	v_cndmask_b32_e64 v163, v163, 1.0, s[30:31]
	v_cndmask_b32_e64 v169, v180, 1.0, s[30:31]
	v_cndmask_b32_e64 v164, v164, 1.0, s[30:31]
	v_cndmask_b32_e64 v170, v181, 1.0, s[30:31]
	v_cndmask_b32_e64 v167, v167, 1.0, s[30:31]
	v_cndmask_b32_e64 v171, v182, 1.0, s[30:31]
	v_cndmask_b32_e64 v168, v168, 1.0, s[30:31]
	v_cndmask_b32_e64 v172, v183, 1.0, s[30:31]
	v_mul_f32_e32 v180, v163, v147
	v_mul_f32_e32 v181, v169, v176
	v_mul_f32_e32 v182, v164, v162
	v_mul_f32_e32 v183, v170, v177
	v_mul_f32_e32 v176, v167, v165
	v_mul_f32_e32 v177, v171, v178
	v_mul_f32_e32 v178, v168, v166
	v_mul_f32_e32 v179, v172, v179
	v_pk_mul_f32 v[72:73], v[72:73], v[182:183]
	v_pk_mul_f32 v[70:71], v[70:71], v[180:181]
	v_pk_mul_f32 v[68:69], v[68:69], v[178:179]
	v_pk_mul_f32 v[66:67], v[66:67], v[176:177]
	s_cbranch_vccnz .LBB0_1088
	v_lshl_add_u64 v[150:151], v[144:145], 1, v[150:151]
	v_cvt_pk_bf16_f32 v180, v70, v71
	v_cvt_pk_bf16_f32 v181, v72, v73
	v_cvt_pk_bf16_f32 v182, v66, v67
	v_cvt_pk_bf16_f32 v183, v68, v69
	global_store_dwordx4 v[150:151], v[180:183], off offset:256
.LBB0_1088:
	v_or_b32_e32 v150, 32, v146
	s_nop 0
	v_mov_b64_e32 v[152:153], s[8:9]
	v_mad_i64_i32 v[152:153], s[38:39], v150, s85, v[152:153]
	v_lshl_add_u64 v[154:155], v[152:153], 0, s[88:89]
	v_lshl_add_u64 v[152:153], s[34:35], 1, v[154:155]
	v_lshl_add_u64 v[154:155], s[36:37], 1, v[154:155]
	v_lshl_add_u64 v[152:153], v[152:153], 0, v[148:149]
	v_lshl_add_u64 v[154:155], v[154:155], 0, v[148:149]
	global_load_dwordx4 v[158:161], v[152:153], off
	global_load_dwordx4 v[162:165], v[154:155], off
	global_load_dwordx4 v[176:179], v[152:153], off offset:256
	global_load_dwordx4 v[180:183], v[154:155], off offset:256
	v_ashrrev_i32_e32 v151, 31, v150
	v_lshlrev_b64 v[150:151], 11, v[150:151]
	s_and_b64 vcc, exec, s[6:7]
	v_lshl_add_u64 v[150:151], s[10:11], 0, v[150:151]
	s_waitcnt vmcnt(3)
	v_lshlrev_b32_e32 v147, 16, v158
	v_and_b32_e32 v166, 0xffff0000, v158
	v_lshlrev_b32_e32 v167, 16, v159
	v_and_b32_e32 v168, 0xffff0000, v159
	s_waitcnt vmcnt(2)
	v_lshlrev_b32_e32 v158, 16, v162
	v_and_b32_e32 v159, 0xffff0000, v162
	v_lshlrev_b32_e32 v162, 16, v163
	v_and_b32_e32 v163, 0xffff0000, v163
	v_lshlrev_b32_e32 v169, 16, v160
	v_and_b32_e32 v170, 0xffff0000, v160
	v_lshlrev_b32_e32 v171, 16, v161
	v_and_b32_e32 v172, 0xffff0000, v161
	v_lshlrev_b32_e32 v160, 16, v164
	v_and_b32_e32 v161, 0xffff0000, v164
	v_lshlrev_b32_e32 v164, 16, v165
	v_and_b32_e32 v165, 0xffff0000, v165
	v_max_f32_e32 v158, 0x1e3ce508, v158
	v_max_f32_e32 v159, 0x1e3ce508, v159
	v_max_f32_e32 v162, 0x1e3ce508, v162
	v_max_f32_e32 v163, 0x1e3ce508, v163
	v_max_f32_e32 v160, 0x1e3ce508, v160
	v_max_f32_e32 v161, 0x1e3ce508, v161
	v_max_f32_e32 v164, 0x1e3ce508, v164
	v_max_f32_e32 v165, 0x1e3ce508, v165
	v_rcp_f32_e32 v158, v158
	v_rcp_f32_e32 v159, v159
	v_rcp_f32_e32 v162, v162
	v_rcp_f32_e32 v163, v163
	v_rcp_f32_e32 v160, v160
	v_rcp_f32_e32 v161, v161
	v_rcp_f32_e32 v164, v164
	v_rcp_f32_e32 v165, v165
	v_cndmask_b32_e64 v158, v158, 1.0, s[30:31]
	v_cndmask_b32_e64 v159, v159, 1.0, s[30:31]
	v_cndmask_b32_e64 v162, v162, 1.0, s[30:31]
	v_cndmask_b32_e64 v163, v163, 1.0, s[30:31]
	v_cndmask_b32_e64 v173, v160, 1.0, s[30:31]
	v_cndmask_b32_e64 v174, v161, 1.0, s[30:31]
	v_cndmask_b32_e64 v164, v164, 1.0, s[30:31]
	v_cndmask_b32_e64 v165, v165, 1.0, s[30:31]
	v_mul_f32_e32 v158, v158, v147
	v_mul_f32_e32 v159, v159, v166
	v_mul_f32_e32 v160, v162, v167
	v_mul_f32_e32 v161, v163, v168
	v_mul_f32_e32 v162, v173, v169
	v_mul_f32_e32 v163, v174, v170
	v_mul_f32_e32 v164, v164, v171
	v_mul_f32_e32 v165, v165, v172
	v_pk_mul_f32 v[96:97], v[96:97], v[160:161]
	v_pk_mul_f32 v[94:95], v[94:95], v[158:159]
	v_pk_mul_f32 v[92:93], v[92:93], v[164:165]
	v_pk_mul_f32 v[90:91], v[90:91], v[162:163]
	s_waitcnt vmcnt(0)
	s_cbranch_vccnz .LBB0_1090
	v_lshl_add_u64 v[162:163], v[144:145], 1, v[150:151]
	v_cvt_pk_bf16_f32 v158, v94, v95
	v_cvt_pk_bf16_f32 v159, v96, v97
	v_cvt_pk_bf16_f32 v160, v90, v91
	v_cvt_pk_bf16_f32 v161, v92, v93
	global_store_dwordx4 v[162:163], v[158:161], off
.LBB0_1090:
	s_and_b64 vcc, exec, s[6:7]
	v_lshlrev_b32_e32 v147, 16, v176
	v_lshlrev_b32_e32 v163, 16, v180
	v_and_b32_e32 v180, 0xffff0000, v180
	v_lshlrev_b32_e32 v164, 16, v181
	v_and_b32_e32 v181, 0xffff0000, v181
	v_lshlrev_b32_e32 v167, 16, v182
	v_and_b32_e32 v182, 0xffff0000, v182
	v_lshlrev_b32_e32 v168, 16, v183
	v_and_b32_e32 v183, 0xffff0000, v183
	v_max_f32_e32 v163, 0x1e3ce508, v163
	v_max_f32_e32 v180, 0x1e3ce508, v180
	v_max_f32_e32 v164, 0x1e3ce508, v164
	v_max_f32_e32 v181, 0x1e3ce508, v181
	v_max_f32_e32 v167, 0x1e3ce508, v167
	v_max_f32_e32 v182, 0x1e3ce508, v182
	v_max_f32_e32 v168, 0x1e3ce508, v168
	v_max_f32_e32 v183, 0x1e3ce508, v183
	v_rcp_f32_e32 v163, v163
	v_rcp_f32_e32 v180, v180
	v_rcp_f32_e32 v164, v164
	v_rcp_f32_e32 v181, v181
	v_rcp_f32_e32 v167, v167
	v_rcp_f32_e32 v182, v182
	v_rcp_f32_e32 v168, v168
	v_rcp_f32_e32 v183, v183
	v_and_b32_e32 v176, 0xffff0000, v176
	v_lshlrev_b32_e32 v162, 16, v177
	v_and_b32_e32 v177, 0xffff0000, v177
	v_lshlrev_b32_e32 v165, 16, v178
	v_and_b32_e32 v178, 0xffff0000, v178
	v_lshlrev_b32_e32 v166, 16, v179
	v_and_b32_e32 v179, 0xffff0000, v179
	v_cndmask_b32_e64 v163, v163, 1.0, s[30:31]
	v_cndmask_b32_e64 v169, v180, 1.0, s[30:31]
	v_cndmask_b32_e64 v164, v164, 1.0, s[30:31]
	v_cndmask_b32_e64 v170, v181, 1.0, s[30:31]
	v_cndmask_b32_e64 v167, v167, 1.0, s[30:31]
	v_cndmask_b32_e64 v171, v182, 1.0, s[30:31]
	v_cndmask_b32_e64 v168, v168, 1.0, s[30:31]
	v_cndmask_b32_e64 v172, v183, 1.0, s[30:31]
	v_mul_f32_e32 v180, v163, v147
	v_mul_f32_e32 v181, v169, v176
	v_mul_f32_e32 v182, v164, v162
	v_mul_f32_e32 v183, v170, v177
	v_mul_f32_e32 v176, v167, v165
	v_mul_f32_e32 v177, v171, v178
	v_mul_f32_e32 v178, v168, v166
	v_mul_f32_e32 v179, v172, v179
	v_pk_mul_f32 v[64:65], v[64:65], v[182:183]
	v_pk_mul_f32 v[62:63], v[62:63], v[180:181]
	v_pk_mul_f32 v[60:61], v[60:61], v[178:179]
	v_pk_mul_f32 v[58:59], v[58:59], v[176:177]
	s_cbranch_vccnz .LBB0_1092
	v_lshl_add_u64 v[150:151], v[144:145], 1, v[150:151]
	v_cvt_pk_bf16_f32 v180, v62, v63
	v_cvt_pk_bf16_f32 v181, v64, v65
	v_cvt_pk_bf16_f32 v182, v58, v59
	v_cvt_pk_bf16_f32 v183, v60, v61
	global_store_dwordx4 v[150:151], v[180:183], off offset:256
.LBB0_1092:
	v_or_b32_e32 v150, 48, v146
	s_nop 0
	v_mov_b64_e32 v[152:153], s[8:9]
	v_mad_i64_i32 v[152:153], s[38:39], v150, s85, v[152:153]
	v_lshl_add_u64 v[154:155], v[152:153], 0, s[88:89]
	v_lshl_add_u64 v[152:153], s[34:35], 1, v[154:155]
	v_lshl_add_u64 v[154:155], s[36:37], 1, v[154:155]
	v_lshl_add_u64 v[152:153], v[152:153], 0, v[148:149]
	v_lshl_add_u64 v[154:155], v[154:155], 0, v[148:149]
	global_load_dwordx4 v[158:161], v[152:153], off
	global_load_dwordx4 v[162:165], v[154:155], off
	global_load_dwordx4 v[176:179], v[152:153], off offset:256
	global_load_dwordx4 v[180:183], v[154:155], off offset:256
	v_ashrrev_i32_e32 v151, 31, v150
	v_lshlrev_b64 v[150:151], 11, v[150:151]
	s_and_b64 vcc, exec, s[6:7]
	v_lshl_add_u64 v[150:151], s[10:11], 0, v[150:151]
	s_waitcnt vmcnt(3)
	v_lshlrev_b32_e32 v147, 16, v158
	v_and_b32_e32 v166, 0xffff0000, v158
	v_lshlrev_b32_e32 v167, 16, v159
	v_and_b32_e32 v168, 0xffff0000, v159
	s_waitcnt vmcnt(2)
	v_lshlrev_b32_e32 v158, 16, v162
	v_and_b32_e32 v159, 0xffff0000, v162
	v_lshlrev_b32_e32 v162, 16, v163
	v_and_b32_e32 v163, 0xffff0000, v163
	v_lshlrev_b32_e32 v169, 16, v160
	v_and_b32_e32 v170, 0xffff0000, v160
	v_lshlrev_b32_e32 v171, 16, v161
	v_and_b32_e32 v172, 0xffff0000, v161
	v_lshlrev_b32_e32 v160, 16, v164
	v_and_b32_e32 v161, 0xffff0000, v164
	v_lshlrev_b32_e32 v164, 16, v165
	v_and_b32_e32 v165, 0xffff0000, v165
	v_max_f32_e32 v158, 0x1e3ce508, v158
	v_max_f32_e32 v159, 0x1e3ce508, v159
	v_max_f32_e32 v162, 0x1e3ce508, v162
	v_max_f32_e32 v163, 0x1e3ce508, v163
	v_max_f32_e32 v160, 0x1e3ce508, v160
	v_max_f32_e32 v161, 0x1e3ce508, v161
	v_max_f32_e32 v164, 0x1e3ce508, v164
	v_max_f32_e32 v165, 0x1e3ce508, v165
	v_rcp_f32_e32 v158, v158
	v_rcp_f32_e32 v159, v159
	v_rcp_f32_e32 v162, v162
	v_rcp_f32_e32 v163, v163
	v_rcp_f32_e32 v160, v160
	v_rcp_f32_e32 v161, v161
	v_rcp_f32_e32 v164, v164
	v_rcp_f32_e32 v165, v165
	v_cndmask_b32_e64 v158, v158, 1.0, s[30:31]
	v_cndmask_b32_e64 v159, v159, 1.0, s[30:31]
	v_cndmask_b32_e64 v162, v162, 1.0, s[30:31]
	v_cndmask_b32_e64 v163, v163, 1.0, s[30:31]
	v_cndmask_b32_e64 v173, v160, 1.0, s[30:31]
	v_cndmask_b32_e64 v174, v161, 1.0, s[30:31]
	v_cndmask_b32_e64 v164, v164, 1.0, s[30:31]
	v_cndmask_b32_e64 v165, v165, 1.0, s[30:31]
	v_mul_f32_e32 v158, v158, v147
	v_mul_f32_e32 v159, v159, v166
	v_mul_f32_e32 v160, v162, v167
	v_mul_f32_e32 v161, v163, v168
	v_mul_f32_e32 v162, v173, v169
	v_mul_f32_e32 v163, v174, v170
	v_mul_f32_e32 v164, v164, v171
	v_mul_f32_e32 v165, v165, v172
	v_pk_mul_f32 v[88:89], v[88:89], v[160:161]
	v_pk_mul_f32 v[86:87], v[86:87], v[158:159]
	v_pk_mul_f32 v[84:85], v[84:85], v[164:165]
	v_pk_mul_f32 v[82:83], v[82:83], v[162:163]
	s_waitcnt vmcnt(0)
	s_cbranch_vccnz .LBB0_1094
	v_lshl_add_u64 v[162:163], v[144:145], 1, v[150:151]
	v_cvt_pk_bf16_f32 v158, v86, v87
	v_cvt_pk_bf16_f32 v159, v88, v89
	v_cvt_pk_bf16_f32 v160, v82, v83
	v_cvt_pk_bf16_f32 v161, v84, v85
	global_store_dwordx4 v[162:163], v[158:161], off
.LBB0_1094:
	s_and_b64 vcc, exec, s[6:7]
	v_lshlrev_b32_e32 v147, 16, v176
	v_lshlrev_b32_e32 v163, 16, v180
	v_and_b32_e32 v180, 0xffff0000, v180
	v_lshlrev_b32_e32 v164, 16, v181
	v_and_b32_e32 v181, 0xffff0000, v181
	v_lshlrev_b32_e32 v167, 16, v182
	v_and_b32_e32 v182, 0xffff0000, v182
	v_lshlrev_b32_e32 v168, 16, v183
	v_and_b32_e32 v183, 0xffff0000, v183
	v_max_f32_e32 v163, 0x1e3ce508, v163
	v_max_f32_e32 v180, 0x1e3ce508, v180
	v_max_f32_e32 v164, 0x1e3ce508, v164
	v_max_f32_e32 v181, 0x1e3ce508, v181
	v_max_f32_e32 v167, 0x1e3ce508, v167
	v_max_f32_e32 v182, 0x1e3ce508, v182
	v_max_f32_e32 v168, 0x1e3ce508, v168
	v_max_f32_e32 v183, 0x1e3ce508, v183
	v_rcp_f32_e32 v163, v163
	v_rcp_f32_e32 v180, v180
	v_rcp_f32_e32 v164, v164
	v_rcp_f32_e32 v181, v181
	v_rcp_f32_e32 v167, v167
	v_rcp_f32_e32 v182, v182
	v_rcp_f32_e32 v168, v168
	v_rcp_f32_e32 v183, v183
	v_and_b32_e32 v176, 0xffff0000, v176
	v_lshlrev_b32_e32 v162, 16, v177
	v_and_b32_e32 v177, 0xffff0000, v177
	v_lshlrev_b32_e32 v165, 16, v178
	v_and_b32_e32 v178, 0xffff0000, v178
	v_lshlrev_b32_e32 v166, 16, v179
	v_and_b32_e32 v179, 0xffff0000, v179
	v_cndmask_b32_e64 v163, v163, 1.0, s[30:31]
	v_cndmask_b32_e64 v169, v180, 1.0, s[30:31]
	v_cndmask_b32_e64 v164, v164, 1.0, s[30:31]
	v_cndmask_b32_e64 v170, v181, 1.0, s[30:31]
	v_cndmask_b32_e64 v167, v167, 1.0, s[30:31]
	v_cndmask_b32_e64 v171, v182, 1.0, s[30:31]
	v_cndmask_b32_e64 v168, v168, 1.0, s[30:31]
	v_cndmask_b32_e64 v172, v183, 1.0, s[30:31]
	v_mul_f32_e32 v180, v163, v147
	v_mul_f32_e32 v181, v169, v176
	v_mul_f32_e32 v182, v164, v162
	v_mul_f32_e32 v183, v170, v177
	v_mul_f32_e32 v176, v167, v165
	v_mul_f32_e32 v177, v171, v178
	v_mul_f32_e32 v178, v168, v166
	v_mul_f32_e32 v179, v172, v179
	v_pk_mul_f32 v[56:57], v[56:57], v[182:183]
	v_pk_mul_f32 v[54:55], v[54:55], v[180:181]
	v_pk_mul_f32 v[52:53], v[52:53], v[178:179]
	v_pk_mul_f32 v[50:51], v[50:51], v[176:177]
	s_cbranch_vccnz .LBB0_1096
	v_lshl_add_u64 v[150:151], v[144:145], 1, v[150:151]
	v_cvt_pk_bf16_f32 v180, v54, v55
	v_cvt_pk_bf16_f32 v181, v56, v57
	v_cvt_pk_bf16_f32 v182, v50, v51
	v_cvt_pk_bf16_f32 v183, v52, v53
	global_store_dwordx4 v[150:151], v[180:183], off offset:256
.LBB0_1096:
	v_add_u32_e32 v150, 0x80, v146
	s_nop 0
	v_mov_b64_e32 v[152:153], s[8:9]
	v_mad_i64_i32 v[152:153], s[38:39], v150, s85, v[152:153]
	v_lshl_add_u64 v[154:155], v[152:153], 0, s[88:89]
	v_lshl_add_u64 v[152:153], s[34:35], 1, v[154:155]
	v_lshl_add_u64 v[154:155], s[36:37], 1, v[154:155]
	v_lshl_add_u64 v[152:153], v[152:153], 0, v[148:149]
	v_lshl_add_u64 v[154:155], v[154:155], 0, v[148:149]
	global_load_dwordx4 v[158:161], v[152:153], off
	global_load_dwordx4 v[162:165], v[154:155], off
	global_load_dwordx4 v[176:179], v[152:153], off offset:256
	global_load_dwordx4 v[180:183], v[154:155], off offset:256
	v_ashrrev_i32_e32 v151, 31, v150
	v_lshlrev_b64 v[150:151], 11, v[150:151]
	s_and_b64 vcc, exec, s[6:7]
	v_lshl_add_u64 v[150:151], s[10:11], 0, v[150:151]
	s_waitcnt vmcnt(3)
	v_lshlrev_b32_e32 v147, 16, v158
	v_and_b32_e32 v166, 0xffff0000, v158
	v_lshlrev_b32_e32 v167, 16, v159
	v_and_b32_e32 v168, 0xffff0000, v159
	s_waitcnt vmcnt(2)
	v_lshlrev_b32_e32 v158, 16, v162
	v_and_b32_e32 v159, 0xffff0000, v162
	v_lshlrev_b32_e32 v162, 16, v163
	v_and_b32_e32 v163, 0xffff0000, v163
	v_lshlrev_b32_e32 v169, 16, v160
	v_and_b32_e32 v170, 0xffff0000, v160
	v_lshlrev_b32_e32 v171, 16, v161
	v_and_b32_e32 v172, 0xffff0000, v161
	v_lshlrev_b32_e32 v160, 16, v164
	v_and_b32_e32 v161, 0xffff0000, v164
	v_lshlrev_b32_e32 v164, 16, v165
	v_and_b32_e32 v165, 0xffff0000, v165
	v_max_f32_e32 v158, 0x1e3ce508, v158
	v_max_f32_e32 v159, 0x1e3ce508, v159
	v_max_f32_e32 v162, 0x1e3ce508, v162
	v_max_f32_e32 v163, 0x1e3ce508, v163
	v_max_f32_e32 v160, 0x1e3ce508, v160
	v_max_f32_e32 v161, 0x1e3ce508, v161
	v_max_f32_e32 v164, 0x1e3ce508, v164
	v_max_f32_e32 v165, 0x1e3ce508, v165
	v_rcp_f32_e32 v158, v158
	v_rcp_f32_e32 v159, v159
	v_rcp_f32_e32 v162, v162
	v_rcp_f32_e32 v163, v163
	v_rcp_f32_e32 v160, v160
	v_rcp_f32_e32 v161, v161
	v_rcp_f32_e32 v164, v164
	v_rcp_f32_e32 v165, v165
	v_cndmask_b32_e64 v158, v158, 1.0, s[30:31]
	v_cndmask_b32_e64 v159, v159, 1.0, s[30:31]
	v_cndmask_b32_e64 v162, v162, 1.0, s[30:31]
	v_cndmask_b32_e64 v163, v163, 1.0, s[30:31]
	v_cndmask_b32_e64 v173, v160, 1.0, s[30:31]
	v_cndmask_b32_e64 v174, v161, 1.0, s[30:31]
	v_cndmask_b32_e64 v164, v164, 1.0, s[30:31]
	v_cndmask_b32_e64 v165, v165, 1.0, s[30:31]
	v_mul_f32_e32 v158, v158, v147
	v_mul_f32_e32 v159, v159, v166
	v_mul_f32_e32 v160, v162, v167
	v_mul_f32_e32 v161, v163, v168
	v_mul_f32_e32 v162, v173, v169
	v_mul_f32_e32 v163, v174, v170
	v_mul_f32_e32 v164, v164, v171
	v_mul_f32_e32 v165, v165, v172
	v_pk_mul_f32 v[48:49], v[48:49], v[160:161]
	v_pk_mul_f32 v[46:47], v[46:47], v[158:159]
	v_pk_mul_f32 v[44:45], v[44:45], v[164:165]
	v_pk_mul_f32 v[42:43], v[42:43], v[162:163]
	s_waitcnt vmcnt(0)
	s_cbranch_vccnz .LBB0_1098
	v_lshl_add_u64 v[162:163], v[144:145], 1, v[150:151]
	v_cvt_pk_bf16_f32 v158, v46, v47
	v_cvt_pk_bf16_f32 v159, v48, v49
	v_cvt_pk_bf16_f32 v160, v42, v43
	v_cvt_pk_bf16_f32 v161, v44, v45
	global_store_dwordx4 v[162:163], v[158:161], off
.LBB0_1098:
	s_and_b64 vcc, exec, s[6:7]
	v_lshlrev_b32_e32 v147, 16, v176
	v_lshlrev_b32_e32 v163, 16, v180
	v_and_b32_e32 v180, 0xffff0000, v180
	v_lshlrev_b32_e32 v164, 16, v181
	v_and_b32_e32 v181, 0xffff0000, v181
	v_lshlrev_b32_e32 v167, 16, v182
	v_and_b32_e32 v182, 0xffff0000, v182
	v_lshlrev_b32_e32 v168, 16, v183
	v_and_b32_e32 v183, 0xffff0000, v183
	v_max_f32_e32 v163, 0x1e3ce508, v163
	v_max_f32_e32 v180, 0x1e3ce508, v180
	v_max_f32_e32 v164, 0x1e3ce508, v164
	v_max_f32_e32 v181, 0x1e3ce508, v181
	v_max_f32_e32 v167, 0x1e3ce508, v167
	v_max_f32_e32 v182, 0x1e3ce508, v182
	v_max_f32_e32 v168, 0x1e3ce508, v168
	v_max_f32_e32 v183, 0x1e3ce508, v183
	v_rcp_f32_e32 v163, v163
	v_rcp_f32_e32 v180, v180
	v_rcp_f32_e32 v164, v164
	v_rcp_f32_e32 v181, v181
	v_rcp_f32_e32 v167, v167
	v_rcp_f32_e32 v182, v182
	v_rcp_f32_e32 v168, v168
	v_rcp_f32_e32 v183, v183
	v_and_b32_e32 v176, 0xffff0000, v176
	v_lshlrev_b32_e32 v162, 16, v177
	v_and_b32_e32 v177, 0xffff0000, v177
	v_lshlrev_b32_e32 v165, 16, v178
	v_and_b32_e32 v178, 0xffff0000, v178
	v_lshlrev_b32_e32 v166, 16, v179
	v_and_b32_e32 v179, 0xffff0000, v179
	v_cndmask_b32_e64 v163, v163, 1.0, s[30:31]
	v_cndmask_b32_e64 v169, v180, 1.0, s[30:31]
	v_cndmask_b32_e64 v164, v164, 1.0, s[30:31]
	v_cndmask_b32_e64 v170, v181, 1.0, s[30:31]
	v_cndmask_b32_e64 v167, v167, 1.0, s[30:31]
	v_cndmask_b32_e64 v171, v182, 1.0, s[30:31]
	v_cndmask_b32_e64 v168, v168, 1.0, s[30:31]
	v_cndmask_b32_e64 v172, v183, 1.0, s[30:31]
	v_mul_f32_e32 v180, v163, v147
	v_mul_f32_e32 v181, v169, v176
	v_mul_f32_e32 v182, v164, v162
	v_mul_f32_e32 v183, v170, v177
	v_mul_f32_e32 v176, v167, v165
	v_mul_f32_e32 v177, v171, v178
	v_mul_f32_e32 v178, v168, v166
	v_mul_f32_e32 v179, v172, v179
	v_pk_mul_f32 v[16:17], v[16:17], v[182:183]
	v_pk_mul_f32 v[14:15], v[14:15], v[180:181]
	v_pk_mul_f32 v[12:13], v[12:13], v[178:179]
	v_pk_mul_f32 v[10:11], v[10:11], v[176:177]
	s_cbranch_vccnz .LBB0_1100
	v_lshl_add_u64 v[150:151], v[144:145], 1, v[150:151]
	v_cvt_pk_bf16_f32 v180, v14, v15
	v_cvt_pk_bf16_f32 v181, v16, v17
	v_cvt_pk_bf16_f32 v182, v10, v11
	v_cvt_pk_bf16_f32 v183, v12, v13
	global_store_dwordx4 v[150:151], v[180:183], off offset:256
.LBB0_1100:
	v_add_u32_e32 v150, 0x90, v146
	s_nop 0
	v_mov_b64_e32 v[152:153], s[8:9]
	v_mad_i64_i32 v[152:153], s[38:39], v150, s85, v[152:153]
	v_lshl_add_u64 v[154:155], v[152:153], 0, s[88:89]
	v_lshl_add_u64 v[152:153], s[34:35], 1, v[154:155]
	v_lshl_add_u64 v[154:155], s[36:37], 1, v[154:155]
	v_lshl_add_u64 v[152:153], v[152:153], 0, v[148:149]
	v_lshl_add_u64 v[154:155], v[154:155], 0, v[148:149]
	global_load_dwordx4 v[158:161], v[152:153], off
	global_load_dwordx4 v[162:165], v[154:155], off
	global_load_dwordx4 v[176:179], v[152:153], off offset:256
	global_load_dwordx4 v[180:183], v[154:155], off offset:256
	v_ashrrev_i32_e32 v151, 31, v150
	v_lshlrev_b64 v[150:151], 11, v[150:151]
	s_and_b64 vcc, exec, s[6:7]
	v_lshl_add_u64 v[150:151], s[10:11], 0, v[150:151]
	s_waitcnt vmcnt(3)
	v_lshlrev_b32_e32 v147, 16, v158
	v_and_b32_e32 v166, 0xffff0000, v158
	v_lshlrev_b32_e32 v167, 16, v159
	v_and_b32_e32 v168, 0xffff0000, v159
	s_waitcnt vmcnt(2)
	v_lshlrev_b32_e32 v158, 16, v162
	v_and_b32_e32 v159, 0xffff0000, v162
	v_lshlrev_b32_e32 v162, 16, v163
	v_and_b32_e32 v163, 0xffff0000, v163
	v_lshlrev_b32_e32 v169, 16, v160
	v_and_b32_e32 v170, 0xffff0000, v160
	v_lshlrev_b32_e32 v171, 16, v161
	v_and_b32_e32 v172, 0xffff0000, v161
	v_lshlrev_b32_e32 v160, 16, v164
	v_and_b32_e32 v161, 0xffff0000, v164
	v_lshlrev_b32_e32 v164, 16, v165
	v_and_b32_e32 v165, 0xffff0000, v165
	v_max_f32_e32 v158, 0x1e3ce508, v158
	v_max_f32_e32 v159, 0x1e3ce508, v159
	v_max_f32_e32 v162, 0x1e3ce508, v162
	v_max_f32_e32 v163, 0x1e3ce508, v163
	v_max_f32_e32 v160, 0x1e3ce508, v160
	v_max_f32_e32 v161, 0x1e3ce508, v161
	v_max_f32_e32 v164, 0x1e3ce508, v164
	v_max_f32_e32 v165, 0x1e3ce508, v165
	v_rcp_f32_e32 v158, v158
	v_rcp_f32_e32 v159, v159
	v_rcp_f32_e32 v162, v162
	v_rcp_f32_e32 v163, v163
	v_rcp_f32_e32 v160, v160
	v_rcp_f32_e32 v161, v161
	v_rcp_f32_e32 v164, v164
	v_rcp_f32_e32 v165, v165
	v_cndmask_b32_e64 v158, v158, 1.0, s[30:31]
	v_cndmask_b32_e64 v159, v159, 1.0, s[30:31]
	v_cndmask_b32_e64 v162, v162, 1.0, s[30:31]
	v_cndmask_b32_e64 v163, v163, 1.0, s[30:31]
	v_cndmask_b32_e64 v173, v160, 1.0, s[30:31]
	v_cndmask_b32_e64 v174, v161, 1.0, s[30:31]
	v_cndmask_b32_e64 v164, v164, 1.0, s[30:31]
	v_cndmask_b32_e64 v165, v165, 1.0, s[30:31]
	v_mul_f32_e32 v158, v158, v147
	v_mul_f32_e32 v159, v159, v166
	v_mul_f32_e32 v160, v162, v167
	v_mul_f32_e32 v161, v163, v168
	v_mul_f32_e32 v162, v173, v169
	v_mul_f32_e32 v163, v174, v170
	v_mul_f32_e32 v164, v164, v171
	v_mul_f32_e32 v165, v165, v172
	v_pk_mul_f32 v[40:41], v[40:41], v[160:161]
	v_pk_mul_f32 v[38:39], v[38:39], v[158:159]
	v_pk_mul_f32 v[36:37], v[36:37], v[164:165]
	v_pk_mul_f32 v[34:35], v[34:35], v[162:163]
	s_waitcnt vmcnt(0)
	s_cbranch_vccnz .LBB0_1102
	v_lshl_add_u64 v[162:163], v[144:145], 1, v[150:151]
	v_cvt_pk_bf16_f32 v158, v38, v39
	v_cvt_pk_bf16_f32 v159, v40, v41
	v_cvt_pk_bf16_f32 v160, v34, v35
	v_cvt_pk_bf16_f32 v161, v36, v37
	global_store_dwordx4 v[162:163], v[158:161], off
.LBB0_1102:
	s_and_b64 vcc, exec, s[6:7]
	v_lshlrev_b32_e32 v147, 16, v176
	v_lshlrev_b32_e32 v163, 16, v180
	v_and_b32_e32 v180, 0xffff0000, v180
	v_lshlrev_b32_e32 v164, 16, v181
	v_and_b32_e32 v181, 0xffff0000, v181
	v_lshlrev_b32_e32 v167, 16, v182
	v_and_b32_e32 v182, 0xffff0000, v182
	v_lshlrev_b32_e32 v168, 16, v183
	v_and_b32_e32 v183, 0xffff0000, v183
	v_max_f32_e32 v163, 0x1e3ce508, v163
	v_max_f32_e32 v180, 0x1e3ce508, v180
	v_max_f32_e32 v164, 0x1e3ce508, v164
	v_max_f32_e32 v181, 0x1e3ce508, v181
	v_max_f32_e32 v167, 0x1e3ce508, v167
	v_max_f32_e32 v182, 0x1e3ce508, v182
	v_max_f32_e32 v168, 0x1e3ce508, v168
	v_max_f32_e32 v183, 0x1e3ce508, v183
	v_rcp_f32_e32 v163, v163
	v_rcp_f32_e32 v180, v180
	v_rcp_f32_e32 v164, v164
	v_rcp_f32_e32 v181, v181
	v_rcp_f32_e32 v167, v167
	v_rcp_f32_e32 v182, v182
	v_rcp_f32_e32 v168, v168
	v_rcp_f32_e32 v183, v183
	v_and_b32_e32 v176, 0xffff0000, v176
	v_lshlrev_b32_e32 v162, 16, v177
	v_and_b32_e32 v177, 0xffff0000, v177
	v_lshlrev_b32_e32 v165, 16, v178
	v_and_b32_e32 v178, 0xffff0000, v178
	v_lshlrev_b32_e32 v166, 16, v179
	v_and_b32_e32 v179, 0xffff0000, v179
	v_cndmask_b32_e64 v163, v163, 1.0, s[30:31]
	v_cndmask_b32_e64 v169, v180, 1.0, s[30:31]
	v_cndmask_b32_e64 v164, v164, 1.0, s[30:31]
	v_cndmask_b32_e64 v170, v181, 1.0, s[30:31]
	v_cndmask_b32_e64 v167, v167, 1.0, s[30:31]
	v_cndmask_b32_e64 v171, v182, 1.0, s[30:31]
	v_cndmask_b32_e64 v168, v168, 1.0, s[30:31]
	v_cndmask_b32_e64 v172, v183, 1.0, s[30:31]
	v_mul_f32_e32 v180, v163, v147
	v_mul_f32_e32 v181, v169, v176
	v_mul_f32_e32 v182, v164, v162
	v_mul_f32_e32 v183, v170, v177
	v_mul_f32_e32 v176, v167, v165
	v_mul_f32_e32 v177, v171, v178
	v_mul_f32_e32 v178, v168, v166
	v_mul_f32_e32 v179, v172, v179
	v_pk_mul_f32 v[8:9], v[8:9], v[182:183]
	v_pk_mul_f32 v[6:7], v[6:7], v[180:181]
	v_pk_mul_f32 v[4:5], v[4:5], v[178:179]
	v_pk_mul_f32 v[2:3], v[2:3], v[176:177]
	s_cbranch_vccnz .LBB0_1104
	v_lshl_add_u64 v[150:151], v[144:145], 1, v[150:151]
	v_cvt_pk_bf16_f32 v180, v6, v7
	v_cvt_pk_bf16_f32 v181, v8, v9
	v_cvt_pk_bf16_f32 v182, v2, v3
	v_cvt_pk_bf16_f32 v183, v4, v5
	global_store_dwordx4 v[150:151], v[180:183], off offset:256
.LBB0_1104:
	v_add_u32_e32 v150, 0xa0, v146
	s_nop 0
	v_mov_b64_e32 v[152:153], s[8:9]
	v_mad_i64_i32 v[152:153], s[38:39], v150, s85, v[152:153]
	v_lshl_add_u64 v[154:155], v[152:153], 0, s[88:89]
	v_lshl_add_u64 v[152:153], s[34:35], 1, v[154:155]
	v_lshl_add_u64 v[154:155], s[36:37], 1, v[154:155]
	v_lshl_add_u64 v[152:153], v[152:153], 0, v[148:149]
	v_lshl_add_u64 v[154:155], v[154:155], 0, v[148:149]
	global_load_dwordx4 v[158:161], v[152:153], off
	global_load_dwordx4 v[162:165], v[154:155], off
	global_load_dwordx4 v[176:179], v[152:153], off offset:256
	global_load_dwordx4 v[180:183], v[154:155], off offset:256
	v_ashrrev_i32_e32 v151, 31, v150
	v_lshlrev_b64 v[150:151], 11, v[150:151]
	s_and_b64 vcc, exec, s[6:7]
	v_lshl_add_u64 v[150:151], s[10:11], 0, v[150:151]
	s_waitcnt vmcnt(3)
	v_lshlrev_b32_e32 v147, 16, v158
	v_and_b32_e32 v166, 0xffff0000, v158
	v_lshlrev_b32_e32 v167, 16, v159
	v_and_b32_e32 v168, 0xffff0000, v159
	s_waitcnt vmcnt(2)
	v_lshlrev_b32_e32 v158, 16, v162
	v_and_b32_e32 v159, 0xffff0000, v162
	v_lshlrev_b32_e32 v162, 16, v163
	v_and_b32_e32 v163, 0xffff0000, v163
	v_lshlrev_b32_e32 v169, 16, v160
	v_and_b32_e32 v170, 0xffff0000, v160
	v_lshlrev_b32_e32 v171, 16, v161
	v_and_b32_e32 v172, 0xffff0000, v161
	v_lshlrev_b32_e32 v160, 16, v164
	v_and_b32_e32 v161, 0xffff0000, v164
	v_lshlrev_b32_e32 v164, 16, v165
	v_and_b32_e32 v165, 0xffff0000, v165
	v_max_f32_e32 v158, 0x1e3ce508, v158
	v_max_f32_e32 v159, 0x1e3ce508, v159
	v_max_f32_e32 v162, 0x1e3ce508, v162
	v_max_f32_e32 v163, 0x1e3ce508, v163
	v_max_f32_e32 v160, 0x1e3ce508, v160
	v_max_f32_e32 v161, 0x1e3ce508, v161
	v_max_f32_e32 v164, 0x1e3ce508, v164
	v_max_f32_e32 v165, 0x1e3ce508, v165
	v_rcp_f32_e32 v158, v158
	v_rcp_f32_e32 v159, v159
	v_rcp_f32_e32 v162, v162
	v_rcp_f32_e32 v163, v163
	v_rcp_f32_e32 v160, v160
	v_rcp_f32_e32 v161, v161
	v_rcp_f32_e32 v164, v164
	v_rcp_f32_e32 v165, v165
	v_cndmask_b32_e64 v158, v158, 1.0, s[30:31]
	v_cndmask_b32_e64 v159, v159, 1.0, s[30:31]
	v_cndmask_b32_e64 v162, v162, 1.0, s[30:31]
	v_cndmask_b32_e64 v163, v163, 1.0, s[30:31]
	v_cndmask_b32_e64 v173, v160, 1.0, s[30:31]
	v_cndmask_b32_e64 v174, v161, 1.0, s[30:31]
	v_cndmask_b32_e64 v164, v164, 1.0, s[30:31]
	v_cndmask_b32_e64 v165, v165, 1.0, s[30:31]
	v_mul_f32_e32 v158, v158, v147
	v_mul_f32_e32 v159, v159, v166
	v_mul_f32_e32 v160, v162, v167
	v_mul_f32_e32 v161, v163, v168
	v_mul_f32_e32 v162, v173, v169
	v_mul_f32_e32 v163, v174, v170
	v_mul_f32_e32 v164, v164, v171
	v_mul_f32_e32 v165, v165, v172
	v_pk_mul_f32 v[32:33], v[32:33], v[160:161]
	v_pk_mul_f32 v[30:31], v[30:31], v[158:159]
	v_pk_mul_f32 v[28:29], v[28:29], v[164:165]
	v_pk_mul_f32 v[26:27], v[26:27], v[162:163]
	s_waitcnt vmcnt(0)
	s_cbranch_vccnz .LBB0_1106
	v_lshl_add_u64 v[162:163], v[144:145], 1, v[150:151]
	v_cvt_pk_bf16_f32 v158, v30, v31
	v_cvt_pk_bf16_f32 v159, v32, v33
	v_cvt_pk_bf16_f32 v160, v26, v27
	v_cvt_pk_bf16_f32 v161, v28, v29
	global_store_dwordx4 v[162:163], v[158:161], off
.LBB0_1106:
	s_and_b64 vcc, exec, s[6:7]
	v_lshlrev_b32_e32 v147, 16, v176
	v_lshlrev_b32_e32 v163, 16, v180
	v_and_b32_e32 v180, 0xffff0000, v180
	v_lshlrev_b32_e32 v164, 16, v181
	v_and_b32_e32 v181, 0xffff0000, v181
	v_lshlrev_b32_e32 v167, 16, v182
	v_and_b32_e32 v182, 0xffff0000, v182
	v_lshlrev_b32_e32 v168, 16, v183
	v_and_b32_e32 v183, 0xffff0000, v183
	v_max_f32_e32 v163, 0x1e3ce508, v163
	v_max_f32_e32 v180, 0x1e3ce508, v180
	v_max_f32_e32 v164, 0x1e3ce508, v164
	v_max_f32_e32 v181, 0x1e3ce508, v181
	v_max_f32_e32 v167, 0x1e3ce508, v167
	v_max_f32_e32 v182, 0x1e3ce508, v182
	v_max_f32_e32 v168, 0x1e3ce508, v168
	v_max_f32_e32 v183, 0x1e3ce508, v183
	v_rcp_f32_e32 v163, v163
	v_rcp_f32_e32 v180, v180
	v_rcp_f32_e32 v164, v164
	v_rcp_f32_e32 v181, v181
	v_rcp_f32_e32 v167, v167
	v_rcp_f32_e32 v182, v182
	v_rcp_f32_e32 v168, v168
	v_rcp_f32_e32 v183, v183
	v_and_b32_e32 v176, 0xffff0000, v176
	v_lshlrev_b32_e32 v162, 16, v177
	v_and_b32_e32 v177, 0xffff0000, v177
	v_lshlrev_b32_e32 v165, 16, v178
	v_and_b32_e32 v178, 0xffff0000, v178
	v_lshlrev_b32_e32 v166, 16, v179
	v_and_b32_e32 v179, 0xffff0000, v179
	v_cndmask_b32_e64 v163, v163, 1.0, s[30:31]
	v_cndmask_b32_e64 v169, v180, 1.0, s[30:31]
	v_cndmask_b32_e64 v164, v164, 1.0, s[30:31]
	v_cndmask_b32_e64 v170, v181, 1.0, s[30:31]
	v_cndmask_b32_e64 v167, v167, 1.0, s[30:31]
	v_cndmask_b32_e64 v171, v182, 1.0, s[30:31]
	v_cndmask_b32_e64 v168, v168, 1.0, s[30:31]
	v_cndmask_b32_e64 v172, v183, 1.0, s[30:31]
	v_mul_f32_e32 v180, v163, v147
	v_mul_f32_e32 v181, v169, v176
	v_mul_f32_e32 v182, v164, v162
	v_mul_f32_e32 v183, v170, v177
	v_mul_f32_e32 v176, v167, v165
	v_mul_f32_e32 v177, v171, v178
	v_mul_f32_e32 v178, v168, v166
	v_mul_f32_e32 v179, v172, v179
	v_pk_mul_f32 v[116:117], v[116:117], v[182:183]
	v_pk_mul_f32 v[114:115], v[114:115], v[180:181]
	v_pk_mul_f32 v[120:121], v[120:121], v[178:179]
	v_pk_mul_f32 v[118:119], v[118:119], v[176:177]
	s_cbranch_vccnz .LBB0_1108
	v_lshl_add_u64 v[150:151], v[144:145], 1, v[150:151]
	v_cvt_pk_bf16_f32 v180, v114, v115
	v_cvt_pk_bf16_f32 v181, v116, v117
	v_cvt_pk_bf16_f32 v182, v118, v119
	v_cvt_pk_bf16_f32 v183, v120, v121
	global_store_dwordx4 v[150:151], v[180:183], off offset:256
.LBB0_1108:
	v_add_u32_e32 v146, 0xb0, v146
	v_mov_b64_e32 v[150:151], s[8:9]
	v_mad_i64_i32 v[150:151], s[38:39], v146, s85, v[150:151]
	v_lshl_add_u64 v[158:159], v[150:151], 0, s[88:89]
	v_lshl_add_u64 v[150:151], s[34:35], 1, v[158:159]
	v_lshl_add_u64 v[158:159], s[36:37], 1, v[158:159]
	v_lshl_add_u64 v[150:151], v[150:151], 0, v[148:149]
	v_lshl_add_u64 v[148:149], v[158:159], 0, v[148:149]
	global_load_dwordx4 v[152:155], v[150:151], off
	global_load_dwordx4 v[158:161], v[148:149], off
	v_ashrrev_i32_e32 v147, 31, v146
	v_lshlrev_b64 v[146:147], 11, v[146:147]
	s_and_b64 vcc, exec, s[6:7]
	v_lshl_add_u64 v[146:147], s[10:11], 0, v[146:147]
	s_waitcnt vmcnt(1)
	v_lshlrev_b32_e32 v162, 16, v152
	v_and_b32_e32 v163, 0xffff0000, v152
	v_lshlrev_b32_e32 v164, 16, v153
	v_and_b32_e32 v165, 0xffff0000, v153
	s_waitcnt vmcnt(0)
	v_lshlrev_b32_e32 v152, 16, v158
	v_and_b32_e32 v153, 0xffff0000, v158
	v_lshlrev_b32_e32 v158, 16, v159
	v_and_b32_e32 v159, 0xffff0000, v159
	v_lshlrev_b32_e32 v166, 16, v154
	v_and_b32_e32 v167, 0xffff0000, v154
	v_lshlrev_b32_e32 v168, 16, v155
	v_and_b32_e32 v169, 0xffff0000, v155
	v_lshlrev_b32_e32 v154, 16, v160
	v_and_b32_e32 v155, 0xffff0000, v160
	v_lshlrev_b32_e32 v160, 16, v161
	v_and_b32_e32 v161, 0xffff0000, v161
	v_max_f32_e32 v152, 0x1e3ce508, v152
	v_max_f32_e32 v153, 0x1e3ce508, v153
	v_max_f32_e32 v158, 0x1e3ce508, v158
	v_max_f32_e32 v159, 0x1e3ce508, v159
	v_max_f32_e32 v154, 0x1e3ce508, v154
	v_max_f32_e32 v155, 0x1e3ce508, v155
	v_max_f32_e32 v160, 0x1e3ce508, v160
	v_max_f32_e32 v161, 0x1e3ce508, v161
	v_rcp_f32_e32 v152, v152
	v_rcp_f32_e32 v153, v153
	v_rcp_f32_e32 v158, v158
	v_rcp_f32_e32 v159, v159
	v_rcp_f32_e32 v154, v154
	v_rcp_f32_e32 v155, v155
	v_rcp_f32_e32 v160, v160
	v_rcp_f32_e32 v161, v161
	v_cndmask_b32_e64 v152, v152, 1.0, s[30:31]
	v_cndmask_b32_e64 v153, v153, 1.0, s[30:31]
	v_cndmask_b32_e64 v158, v158, 1.0, s[30:31]
	v_cndmask_b32_e64 v159, v159, 1.0, s[30:31]
	v_cndmask_b32_e64 v170, v154, 1.0, s[30:31]
	v_cndmask_b32_e64 v171, v155, 1.0, s[30:31]
	v_cndmask_b32_e64 v160, v160, 1.0, s[30:31]
	v_cndmask_b32_e64 v161, v161, 1.0, s[30:31]
	v_mul_f32_e32 v152, v152, v162
	v_mul_f32_e32 v153, v153, v163
	v_mul_f32_e32 v154, v158, v164
	v_mul_f32_e32 v155, v159, v165
	v_mul_f32_e32 v158, v170, v166
	v_mul_f32_e32 v159, v171, v167
	v_mul_f32_e32 v160, v160, v168
	v_mul_f32_e32 v161, v161, v169
	v_pk_mul_f32 v[24:25], v[24:25], v[154:155]
	v_pk_mul_f32 v[22:23], v[22:23], v[152:153]
	v_pk_mul_f32 v[20:21], v[20:21], v[160:161]
	v_pk_mul_f32 v[18:19], v[18:19], v[158:159]
	s_cbranch_vccnz .LBB0_1110
	v_lshl_add_u64 v[158:159], v[144:145], 1, v[146:147]
	v_cvt_pk_bf16_f32 v152, v22, v23
	v_cvt_pk_bf16_f32 v153, v24, v25
	v_cvt_pk_bf16_f32 v154, v18, v19
	v_cvt_pk_bf16_f32 v155, v20, v21
	global_store_dwordx4 v[158:159], v[152:155], off
.LBB0_1110:
	global_load_dwordx4 v[150:153], v[150:151], off offset:256
	s_nop 0
	global_load_dwordx4 v[158:161], v[148:149], off offset:256
	s_and_b64 vcc, exec, s[6:7]
	s_waitcnt vmcnt(1)
	v_lshlrev_b32_e32 v162, 16, v152
	s_waitcnt vmcnt(0)
	v_lshlrev_b32_e32 v154, 16, v158
	v_and_b32_e32 v155, 0xffff0000, v158
	v_lshlrev_b32_e32 v158, 16, v159
	v_and_b32_e32 v159, 0xffff0000, v159
	v_and_b32_e32 v163, 0xffff0000, v152
	v_lshlrev_b32_e32 v164, 16, v153
	v_and_b32_e32 v165, 0xffff0000, v153
	v_lshlrev_b32_e32 v152, 16, v160
	v_and_b32_e32 v153, 0xffff0000, v160
	v_lshlrev_b32_e32 v160, 16, v161
	v_and_b32_e32 v161, 0xffff0000, v161
	v_max_f32_e32 v154, 0x1e3ce508, v154
	v_max_f32_e32 v155, 0x1e3ce508, v155
	v_max_f32_e32 v158, 0x1e3ce508, v158
	v_max_f32_e32 v159, 0x1e3ce508, v159
	v_max_f32_e32 v152, 0x1e3ce508, v152
	v_max_f32_e32 v153, 0x1e3ce508, v153
	v_max_f32_e32 v160, 0x1e3ce508, v160
	v_max_f32_e32 v161, 0x1e3ce508, v161
	v_rcp_f32_e32 v154, v154
	v_rcp_f32_e32 v155, v155
	v_rcp_f32_e32 v158, v158
	v_rcp_f32_e32 v159, v159
	v_rcp_f32_e32 v152, v152
	v_rcp_f32_e32 v153, v153
	v_rcp_f32_e32 v160, v160
	v_rcp_f32_e32 v161, v161
	v_lshlrev_b32_e32 v148, 16, v150
	v_and_b32_e32 v149, 0xffff0000, v150
	v_lshlrev_b32_e32 v150, 16, v151
	v_and_b32_e32 v151, 0xffff0000, v151
	v_cndmask_b32_e64 v154, v154, 1.0, s[30:31]
	v_cndmask_b32_e64 v155, v155, 1.0, s[30:31]
	v_cndmask_b32_e64 v158, v158, 1.0, s[30:31]
	v_cndmask_b32_e64 v159, v159, 1.0, s[30:31]
	v_cndmask_b32_e64 v152, v152, 1.0, s[30:31]
	v_cndmask_b32_e64 v153, v153, 1.0, s[30:31]
	v_cndmask_b32_e64 v160, v160, 1.0, s[30:31]
	v_cndmask_b32_e64 v161, v161, 1.0, s[30:31]
	v_mul_f32_e32 v148, v154, v148
	v_mul_f32_e32 v149, v155, v149
	v_mul_f32_e32 v150, v158, v150
	v_mul_f32_e32 v151, v159, v151
	v_mul_f32_e32 v152, v152, v162
	v_mul_f32_e32 v153, v153, v163
	v_mul_f32_e32 v154, v160, v164
	v_mul_f32_e32 v155, v161, v165
	v_pk_mul_f32 v[124:125], v[124:125], v[150:151]
	v_pk_mul_f32 v[122:123], v[122:123], v[148:149]
	v_pk_mul_f32 v[128:129], v[128:129], v[154:155]
	v_pk_mul_f32 v[126:127], v[126:127], v[152:153]
	s_cbranch_vccnz .LBB0_1112
	v_lshl_add_u64 v[144:145], v[144:145], 1, v[146:147]
	v_cvt_pk_bf16_f32 v148, v122, v123
	v_cvt_pk_bf16_f32 v149, v124, v125
	v_cvt_pk_bf16_f32 v150, v126, v127
	v_cvt_pk_bf16_f32 v151, v128, v129
	global_store_dwordx4 v[144:145], v[148:151], off offset:256

.LBB0_1134:
	s_lshl_b32 s28, s43, 10
	s_add_i32 s13, s28, 0x400
	s_cmp_eq_u32 s43, 2
	s_cselect_b64 s[20:21], -1, 0
	s_and_b64 s[4:5], s[20:21], exec
	v_mbcnt_lo_u32_b32 v80, -1, 0
	v_mbcnt_hi_u32_b32 v80, -1, v80
	s_cselect_b32 s4, 0x800, s13
	s_lshl_b32 s13, s48, 6
	s_lshl_b32 s5, s49, 8
	s_and_b32 s13, s13, 0x7fffff80
	s_add_i32 s13, s13, s5
	v_and_or_b32 v92, v80, 15, s33
	v_ashrrev_i32_e32 v80, 1, v80
	s_lshl_b32 s26, s4, 1
	s_lshl_b32 s4, s24, 8
	v_and_b32_e32 v82, -8, v80
	v_add_u32_e32 v84, s13, v92
	v_mov_b64_e32 v[80:81], s[8:9]
	s_or_b32 s23, s4, s40
	v_mad_i64_i32 v[80:81], s[4:5], v84, s85, v[80:81]
	v_lshl_add_u64 v[88:89], v[80:81], 0, s[88:89]
	v_add_u32_e32 v80, s23, v82
	s_lshl_b32 s86, s43, 11
	v_ashrrev_i32_e32 v81, 31, v80
	s_mov_b32 s27, s87
	v_lshl_add_u64 v[86:87], v[88:89], 0, s[86:87]
	v_lshlrev_b64 v[82:83], 1, v[80:81]
	v_lshl_add_u64 v[88:89], v[88:89], 0, s[26:27]
	v_lshl_add_u64 v[86:87], v[86:87], 0, v[82:83]
	v_lshl_add_u64 v[88:89], v[88:89], 0, v[82:83]
	global_load_dwordx4 v[94:97], v[86:87], off
	global_load_dwordx4 v[98:101], v[88:89], off
	global_load_dwordx4 v[176:179], v[86:87], off offset:256
	global_load_dwordx4 v[180:183], v[88:89], off offset:256
	v_ashrrev_i32_e32 v85, 31, v84
	v_lshlrev_b64 v[84:85], 11, v[84:85]
	s_cmp_lg_u32 s43, 2
	v_lshl_add_u64 v[84:85], s[10:11], 0, v[84:85]
	s_waitcnt vmcnt(2)
	v_lshlrev_b32_e32 v93, 16, v94
	v_and_b32_e32 v102, 0xffff0000, v94
	v_lshlrev_b32_e32 v103, 16, v95
	v_and_b32_e32 v104, 0xffff0000, v95
	v_lshlrev_b32_e32 v94, 16, v98
	v_and_b32_e32 v95, 0xffff0000, v98
	v_lshlrev_b32_e32 v98, 16, v99
	v_and_b32_e32 v99, 0xffff0000, v99
	v_lshlrev_b32_e32 v105, 16, v96
	v_and_b32_e32 v106, 0xffff0000, v96
	v_lshlrev_b32_e32 v107, 16, v97
	v_and_b32_e32 v108, 0xffff0000, v97
	v_lshlrev_b32_e32 v96, 16, v100
	v_and_b32_e32 v97, 0xffff0000, v100
	v_lshlrev_b32_e32 v100, 16, v101
	v_and_b32_e32 v101, 0xffff0000, v101
	v_max_f32_e32 v94, 0x1e3ce508, v94
	v_max_f32_e32 v95, 0x1e3ce508, v95
	v_max_f32_e32 v98, 0x1e3ce508, v98
	v_max_f32_e32 v99, 0x1e3ce508, v99
	v_max_f32_e32 v96, 0x1e3ce508, v96
	v_max_f32_e32 v97, 0x1e3ce508, v97
	v_max_f32_e32 v100, 0x1e3ce508, v100
	v_max_f32_e32 v101, 0x1e3ce508, v101
	v_rcp_f32_e32 v94, v94
	v_rcp_f32_e32 v95, v95
	v_rcp_f32_e32 v98, v98
	v_rcp_f32_e32 v99, v99
	v_rcp_f32_e32 v96, v96
	v_rcp_f32_e32 v97, v97
	v_rcp_f32_e32 v100, v100
	v_rcp_f32_e32 v101, v101
	v_cndmask_b32_e64 v94, v94, 1.0, s[20:21]
	v_cndmask_b32_e64 v95, v95, 1.0, s[20:21]
	v_cndmask_b32_e64 v98, v98, 1.0, s[20:21]
	v_cndmask_b32_e64 v99, v99, 1.0, s[20:21]
	v_cndmask_b32_e64 v109, v96, 1.0, s[20:21]
	v_cndmask_b32_e64 v110, v97, 1.0, s[20:21]
	v_cndmask_b32_e64 v100, v100, 1.0, s[20:21]
	v_cndmask_b32_e64 v101, v101, 1.0, s[20:21]
	v_mul_f32_e32 v94, v94, v93
	v_mul_f32_e32 v95, v95, v102
	v_mul_f32_e32 v96, v98, v103
	v_mul_f32_e32 v97, v99, v104
	v_mul_f32_e32 v98, v109, v105
	v_mul_f32_e32 v99, v110, v106
	v_mul_f32_e32 v100, v100, v107
	v_mul_f32_e32 v101, v101, v108
	v_pk_mul_f32 v[64:65], v[64:65], v[96:97]
	v_pk_mul_f32 v[62:63], v[62:63], v[94:95]
	v_pk_mul_f32 v[60:61], v[60:61], v[100:101]
	v_pk_mul_f32 v[58:59], v[58:59], v[98:99]
	s_waitcnt vmcnt(0)
	s_cbranch_scc1 .LBB0_1136
	v_lshl_add_u64 v[98:99], v[80:81], 1, v[84:85]
	v_cvt_pk_bf16_f32 v94, v62, v63
	v_cvt_pk_bf16_f32 v95, v64, v65
	v_cvt_pk_bf16_f32 v96, v58, v59
	v_cvt_pk_bf16_f32 v97, v60, v61
	global_store_dwordx4 v[98:99], v[94:97], off
.LBB0_1136:
	v_cndmask_b32_e64 v93, 0, 1, s[20:21]
	v_cmp_ne_u32_e64 s[4:5], 1, v93
	s_andn2_b64 vcc, exec, s[20:21]
	v_lshlrev_b32_e32 v93, 16, v176
	v_lshlrev_b32_e32 v99, 16, v180
	v_and_b32_e32 v180, 0xffff0000, v180
	v_lshlrev_b32_e32 v100, 16, v181
	v_and_b32_e32 v181, 0xffff0000, v181
	v_lshlrev_b32_e32 v103, 16, v182
	v_and_b32_e32 v182, 0xffff0000, v182
	v_lshlrev_b32_e32 v104, 16, v183
	v_and_b32_e32 v183, 0xffff0000, v183
	v_max_f32_e32 v99, 0x1e3ce508, v99
	v_max_f32_e32 v180, 0x1e3ce508, v180
	v_max_f32_e32 v100, 0x1e3ce508, v100
	v_max_f32_e32 v181, 0x1e3ce508, v181
	v_max_f32_e32 v103, 0x1e3ce508, v103
	v_max_f32_e32 v182, 0x1e3ce508, v182
	v_max_f32_e32 v104, 0x1e3ce508, v104
	v_max_f32_e32 v183, 0x1e3ce508, v183
	v_rcp_f32_e32 v99, v99
	v_rcp_f32_e32 v180, v180
	v_rcp_f32_e32 v100, v100
	v_rcp_f32_e32 v181, v181
	v_rcp_f32_e32 v103, v103
	v_rcp_f32_e32 v182, v182
	v_rcp_f32_e32 v104, v104
	v_rcp_f32_e32 v183, v183
	v_and_b32_e32 v176, 0xffff0000, v176
	v_lshlrev_b32_e32 v98, 16, v177
	v_and_b32_e32 v177, 0xffff0000, v177
	v_lshlrev_b32_e32 v101, 16, v178
	v_and_b32_e32 v178, 0xffff0000, v178
	v_lshlrev_b32_e32 v102, 16, v179
	v_and_b32_e32 v179, 0xffff0000, v179
	v_cndmask_b32_e64 v99, v99, 1.0, s[20:21]
	v_cndmask_b32_e64 v105, v180, 1.0, s[20:21]
	v_cndmask_b32_e64 v100, v100, 1.0, s[20:21]
	v_cndmask_b32_e64 v106, v181, 1.0, s[20:21]
	v_cndmask_b32_e64 v103, v103, 1.0, s[20:21]
	v_cndmask_b32_e64 v107, v182, 1.0, s[20:21]
	v_cndmask_b32_e64 v104, v104, 1.0, s[20:21]
	v_cndmask_b32_e64 v108, v183, 1.0, s[20:21]
	v_mul_f32_e32 v180, v99, v93
	v_mul_f32_e32 v181, v105, v176
	v_mul_f32_e32 v182, v100, v98
	v_mul_f32_e32 v183, v106, v177
	v_mul_f32_e32 v176, v103, v101
	v_mul_f32_e32 v177, v107, v178
	v_mul_f32_e32 v178, v104, v102
	v_mul_f32_e32 v179, v108, v179
	v_pk_mul_f32 v[32:33], v[32:33], v[182:183]
	v_pk_mul_f32 v[30:31], v[30:31], v[180:181]
	v_pk_mul_f32 v[28:29], v[28:29], v[178:179]
	v_pk_mul_f32 v[26:27], v[26:27], v[176:177]
	s_cbranch_vccnz .LBB0_1138
	v_lshl_add_u64 v[84:85], v[80:81], 1, v[84:85]
	v_cvt_pk_bf16_f32 v180, v30, v31
	v_cvt_pk_bf16_f32 v181, v32, v33
	v_cvt_pk_bf16_f32 v182, v26, v27
	v_cvt_pk_bf16_f32 v183, v28, v29
	global_store_dwordx4 v[84:85], v[180:183], off offset:256
.LBB0_1138:
	v_add3_u32 v84, v92, s13, 16
	s_nop 0
	v_mov_b64_e32 v[86:87], s[8:9]
	v_mad_i64_i32 v[86:87], s[44:45], v84, s85, v[86:87]
	v_lshl_add_u64 v[88:89], v[86:87], 0, s[88:89]
	s_lshl_b32 s86, s28, 1
	s_mov_b32 s27, s87
	v_lshl_add_u64 v[86:87], v[88:89], 0, s[86:87]
	v_lshl_add_u64 v[88:89], v[88:89], 0, s[26:27]
	v_lshl_add_u64 v[86:87], v[86:87], 0, v[82:83]
	v_lshl_add_u64 v[88:89], v[88:89], 0, v[82:83]
	global_load_dwordx4 v[94:97], v[86:87], off
	global_load_dwordx4 v[98:101], v[88:89], off
	global_load_dwordx4 v[176:179], v[86:87], off offset:256
	global_load_dwordx4 v[180:183], v[88:89], off offset:256
	v_ashrrev_i32_e32 v85, 31, v84
	v_lshlrev_b64 v[84:85], 11, v[84:85]
	s_and_b64 vcc, exec, s[4:5]
	v_lshl_add_u64 v[84:85], s[10:11], 0, v[84:85]
	s_waitcnt vmcnt(2)
	v_lshlrev_b32_e32 v93, 16, v94
	v_and_b32_e32 v102, 0xffff0000, v94
	v_lshlrev_b32_e32 v103, 16, v95
	v_and_b32_e32 v104, 0xffff0000, v95
	v_lshlrev_b32_e32 v94, 16, v98
	v_and_b32_e32 v95, 0xffff0000, v98
	v_lshlrev_b32_e32 v98, 16, v99
	v_and_b32_e32 v99, 0xffff0000, v99
	v_lshlrev_b32_e32 v105, 16, v96
	v_and_b32_e32 v106, 0xffff0000, v96
	v_lshlrev_b32_e32 v107, 16, v97
	v_and_b32_e32 v108, 0xffff0000, v97
	v_lshlrev_b32_e32 v96, 16, v100
	v_and_b32_e32 v97, 0xffff0000, v100
	v_lshlrev_b32_e32 v100, 16, v101
	v_and_b32_e32 v101, 0xffff0000, v101
	v_max_f32_e32 v94, 0x1e3ce508, v94
	v_max_f32_e32 v95, 0x1e3ce508, v95
	v_max_f32_e32 v98, 0x1e3ce508, v98
	v_max_f32_e32 v99, 0x1e3ce508, v99
	v_max_f32_e32 v96, 0x1e3ce508, v96
	v_max_f32_e32 v97, 0x1e3ce508, v97
	v_max_f32_e32 v100, 0x1e3ce508, v100
	v_max_f32_e32 v101, 0x1e3ce508, v101
	v_rcp_f32_e32 v94, v94
	v_rcp_f32_e32 v95, v95
	v_rcp_f32_e32 v98, v98
	v_rcp_f32_e32 v99, v99
	v_rcp_f32_e32 v96, v96
	v_rcp_f32_e32 v97, v97
	v_rcp_f32_e32 v100, v100
	v_rcp_f32_e32 v101, v101
	v_cndmask_b32_e64 v94, v94, 1.0, s[20:21]
	v_cndmask_b32_e64 v95, v95, 1.0, s[20:21]
	v_cndmask_b32_e64 v98, v98, 1.0, s[20:21]
	v_cndmask_b32_e64 v99, v99, 1.0, s[20:21]
	v_cndmask_b32_e64 v109, v96, 1.0, s[20:21]
	v_cndmask_b32_e64 v110, v97, 1.0, s[20:21]
	v_cndmask_b32_e64 v100, v100, 1.0, s[20:21]
	v_cndmask_b32_e64 v101, v101, 1.0, s[20:21]
	v_mul_f32_e32 v94, v94, v93
	v_mul_f32_e32 v95, v95, v102
	v_mul_f32_e32 v96, v98, v103
	v_mul_f32_e32 v97, v99, v104
	v_mul_f32_e32 v98, v109, v105
	v_mul_f32_e32 v99, v110, v106
	v_mul_f32_e32 v100, v100, v107
	v_mul_f32_e32 v101, v101, v108
	v_pk_mul_f32 v[56:57], v[56:57], v[96:97]
	v_pk_mul_f32 v[54:55], v[54:55], v[94:95]
	v_pk_mul_f32 v[52:53], v[52:53], v[100:101]
	v_pk_mul_f32 v[50:51], v[50:51], v[98:99]
	s_waitcnt vmcnt(0)
	s_cbranch_vccnz .LBB0_1140
	v_lshl_add_u64 v[98:99], v[80:81], 1, v[84:85]
	v_cvt_pk_bf16_f32 v94, v54, v55
	v_cvt_pk_bf16_f32 v95, v56, v57
	v_cvt_pk_bf16_f32 v96, v50, v51
	v_cvt_pk_bf16_f32 v97, v52, v53
	global_store_dwordx4 v[98:99], v[94:97], off
.LBB0_1140:
	s_and_b64 vcc, exec, s[4:5]
	v_lshlrev_b32_e32 v93, 16, v176
	v_lshlrev_b32_e32 v99, 16, v180
	v_and_b32_e32 v180, 0xffff0000, v180
	v_lshlrev_b32_e32 v100, 16, v181
	v_and_b32_e32 v181, 0xffff0000, v181
	v_lshlrev_b32_e32 v103, 16, v182
	v_and_b32_e32 v182, 0xffff0000, v182
	v_lshlrev_b32_e32 v104, 16, v183
	v_and_b32_e32 v183, 0xffff0000, v183
	v_max_f32_e32 v99, 0x1e3ce508, v99
	v_max_f32_e32 v180, 0x1e3ce508, v180
	v_max_f32_e32 v100, 0x1e3ce508, v100
	v_max_f32_e32 v181, 0x1e3ce508, v181
	v_max_f32_e32 v103, 0x1e3ce508, v103
	v_max_f32_e32 v182, 0x1e3ce508, v182
	v_max_f32_e32 v104, 0x1e3ce508, v104
	v_max_f32_e32 v183, 0x1e3ce508, v183
	v_rcp_f32_e32 v99, v99
	v_rcp_f32_e32 v180, v180
	v_rcp_f32_e32 v100, v100
	v_rcp_f32_e32 v181, v181
	v_rcp_f32_e32 v103, v103
	v_rcp_f32_e32 v182, v182
	v_rcp_f32_e32 v104, v104
	v_rcp_f32_e32 v183, v183
	v_and_b32_e32 v176, 0xffff0000, v176
	v_lshlrev_b32_e32 v98, 16, v177
	v_and_b32_e32 v177, 0xffff0000, v177
	v_lshlrev_b32_e32 v101, 16, v178
	v_and_b32_e32 v178, 0xffff0000, v178
	v_lshlrev_b32_e32 v102, 16, v179
	v_and_b32_e32 v179, 0xffff0000, v179
	v_cndmask_b32_e64 v99, v99, 1.0, s[20:21]
	v_cndmask_b32_e64 v105, v180, 1.0, s[20:21]
	v_cndmask_b32_e64 v100, v100, 1.0, s[20:21]
	v_cndmask_b32_e64 v106, v181, 1.0, s[20:21]
	v_cndmask_b32_e64 v103, v103, 1.0, s[20:21]
	v_cndmask_b32_e64 v107, v182, 1.0, s[20:21]
	v_cndmask_b32_e64 v104, v104, 1.0, s[20:21]
	v_cndmask_b32_e64 v108, v183, 1.0, s[20:21]
	v_mul_f32_e32 v180, v99, v93
	v_mul_f32_e32 v181, v105, v176
	v_mul_f32_e32 v182, v100, v98
	v_mul_f32_e32 v183, v106, v177
	v_mul_f32_e32 v176, v103, v101
	v_mul_f32_e32 v177, v107, v178
	v_mul_f32_e32 v178, v104, v102
	v_mul_f32_e32 v179, v108, v179
	v_pk_mul_f32 v[24:25], v[24:25], v[182:183]
	v_pk_mul_f32 v[22:23], v[22:23], v[180:181]
	v_pk_mul_f32 v[20:21], v[20:21], v[178:179]
	v_pk_mul_f32 v[18:19], v[18:19], v[176:177]
	s_cbranch_vccnz .LBB0_1142
	v_lshl_add_u64 v[84:85], v[80:81], 1, v[84:85]
	v_cvt_pk_bf16_f32 v180, v22, v23
	v_cvt_pk_bf16_f32 v181, v24, v25
	v_cvt_pk_bf16_f32 v182, v18, v19
	v_cvt_pk_bf16_f32 v183, v20, v21
	global_store_dwordx4 v[84:85], v[180:183], off offset:256
.LBB0_1142:
	v_add3_u32 v84, v92, s13, 32
	s_nop 0
	v_mov_b64_e32 v[86:87], s[8:9]
	v_mad_i64_i32 v[86:87], s[28:29], v84, s85, v[86:87]
	v_lshl_add_u64 v[88:89], v[86:87], 0, s[88:89]
	s_mov_b32 s27, s87
	v_lshl_add_u64 v[86:87], v[88:89], 0, s[86:87]
	v_lshl_add_u64 v[88:89], v[88:89], 0, s[26:27]
	v_lshl_add_u64 v[86:87], v[86:87], 0, v[82:83]
	v_lshl_add_u64 v[88:89], v[88:89], 0, v[82:83]
	global_load_dwordx4 v[94:97], v[86:87], off
	global_load_dwordx4 v[98:101], v[88:89], off
	global_load_dwordx4 v[176:179], v[86:87], off offset:256
	global_load_dwordx4 v[180:183], v[88:89], off offset:256
	v_ashrrev_i32_e32 v85, 31, v84
	v_lshlrev_b64 v[84:85], 11, v[84:85]
	s_and_b64 vcc, exec, s[4:5]
	v_lshl_add_u64 v[84:85], s[10:11], 0, v[84:85]
	s_waitcnt vmcnt(2)
	v_lshlrev_b32_e32 v93, 16, v94
	v_and_b32_e32 v102, 0xffff0000, v94
	v_lshlrev_b32_e32 v103, 16, v95
	v_and_b32_e32 v104, 0xffff0000, v95
	v_lshlrev_b32_e32 v94, 16, v98
	v_and_b32_e32 v95, 0xffff0000, v98
	v_lshlrev_b32_e32 v98, 16, v99
	v_and_b32_e32 v99, 0xffff0000, v99
	v_lshlrev_b32_e32 v105, 16, v96
	v_and_b32_e32 v106, 0xffff0000, v96
	v_lshlrev_b32_e32 v107, 16, v97
	v_and_b32_e32 v108, 0xffff0000, v97
	v_lshlrev_b32_e32 v96, 16, v100
	v_and_b32_e32 v97, 0xffff0000, v100
	v_lshlrev_b32_e32 v100, 16, v101
	v_and_b32_e32 v101, 0xffff0000, v101
	v_max_f32_e32 v94, 0x1e3ce508, v94
	v_max_f32_e32 v95, 0x1e3ce508, v95
	v_max_f32_e32 v98, 0x1e3ce508, v98
	v_max_f32_e32 v99, 0x1e3ce508, v99
	v_max_f32_e32 v96, 0x1e3ce508, v96
	v_max_f32_e32 v97, 0x1e3ce508, v97
	v_max_f32_e32 v100, 0x1e3ce508, v100
	v_max_f32_e32 v101, 0x1e3ce508, v101
	v_rcp_f32_e32 v94, v94
	v_rcp_f32_e32 v95, v95
	v_rcp_f32_e32 v98, v98
	v_rcp_f32_e32 v99, v99
	v_rcp_f32_e32 v96, v96
	v_rcp_f32_e32 v97, v97
	v_rcp_f32_e32 v100, v100
	v_rcp_f32_e32 v101, v101
	v_cndmask_b32_e64 v94, v94, 1.0, s[20:21]
	v_cndmask_b32_e64 v95, v95, 1.0, s[20:21]
	v_cndmask_b32_e64 v98, v98, 1.0, s[20:21]
	v_cndmask_b32_e64 v99, v99, 1.0, s[20:21]
	v_cndmask_b32_e64 v109, v96, 1.0, s[20:21]
	v_cndmask_b32_e64 v110, v97, 1.0, s[20:21]
	v_cndmask_b32_e64 v100, v100, 1.0, s[20:21]
	v_cndmask_b32_e64 v101, v101, 1.0, s[20:21]
	v_mul_f32_e32 v94, v94, v93
	v_mul_f32_e32 v95, v95, v102
	v_mul_f32_e32 v96, v98, v103
	v_mul_f32_e32 v97, v99, v104
	v_mul_f32_e32 v98, v109, v105
	v_mul_f32_e32 v99, v110, v106
	v_mul_f32_e32 v100, v100, v107
	v_mul_f32_e32 v101, v101, v108
	v_pk_mul_f32 v[48:49], v[48:49], v[96:97]
	v_pk_mul_f32 v[46:47], v[46:47], v[94:95]
	v_pk_mul_f32 v[44:45], v[44:45], v[100:101]
	v_pk_mul_f32 v[42:43], v[42:43], v[98:99]
	s_waitcnt vmcnt(0)
	s_cbranch_vccnz .LBB0_1144
	v_lshl_add_u64 v[98:99], v[80:81], 1, v[84:85]
	v_cvt_pk_bf16_f32 v94, v46, v47
	v_cvt_pk_bf16_f32 v95, v48, v49
	v_cvt_pk_bf16_f32 v96, v42, v43
	v_cvt_pk_bf16_f32 v97, v44, v45
	global_store_dwordx4 v[98:99], v[94:97], off
.LBB0_1144:
	s_and_b64 vcc, exec, s[4:5]
	v_lshlrev_b32_e32 v93, 16, v176
	v_lshlrev_b32_e32 v99, 16, v180
	v_and_b32_e32 v180, 0xffff0000, v180
	v_lshlrev_b32_e32 v100, 16, v181
	v_and_b32_e32 v181, 0xffff0000, v181
	v_lshlrev_b32_e32 v103, 16, v182
	v_and_b32_e32 v182, 0xffff0000, v182
	v_lshlrev_b32_e32 v104, 16, v183
	v_and_b32_e32 v183, 0xffff0000, v183
	v_max_f32_e32 v99, 0x1e3ce508, v99
	v_max_f32_e32 v180, 0x1e3ce508, v180
	v_max_f32_e32 v100, 0x1e3ce508, v100
	v_max_f32_e32 v181, 0x1e3ce508, v181
	v_max_f32_e32 v103, 0x1e3ce508, v103
	v_max_f32_e32 v182, 0x1e3ce508, v182
	v_max_f32_e32 v104, 0x1e3ce508, v104
	v_max_f32_e32 v183, 0x1e3ce508, v183
	v_rcp_f32_e32 v99, v99
	v_rcp_f32_e32 v180, v180
	v_rcp_f32_e32 v100, v100
	v_rcp_f32_e32 v181, v181
	v_rcp_f32_e32 v103, v103
	v_rcp_f32_e32 v182, v182
	v_rcp_f32_e32 v104, v104
	v_rcp_f32_e32 v183, v183
	v_and_b32_e32 v176, 0xffff0000, v176
	v_lshlrev_b32_e32 v98, 16, v177
	v_and_b32_e32 v177, 0xffff0000, v177
	v_lshlrev_b32_e32 v101, 16, v178
	v_and_b32_e32 v178, 0xffff0000, v178
	v_lshlrev_b32_e32 v102, 16, v179
	v_and_b32_e32 v179, 0xffff0000, v179
	v_cndmask_b32_e64 v99, v99, 1.0, s[20:21]
	v_cndmask_b32_e64 v105, v180, 1.0, s[20:21]
	v_cndmask_b32_e64 v100, v100, 1.0, s[20:21]
	v_cndmask_b32_e64 v106, v181, 1.0, s[20:21]
	v_cndmask_b32_e64 v103, v103, 1.0, s[20:21]
	v_cndmask_b32_e64 v107, v182, 1.0, s[20:21]
	v_cndmask_b32_e64 v104, v104, 1.0, s[20:21]
	v_cndmask_b32_e64 v108, v183, 1.0, s[20:21]
	v_mul_f32_e32 v180, v99, v93
	v_mul_f32_e32 v181, v105, v176
	v_mul_f32_e32 v182, v100, v98
	v_mul_f32_e32 v183, v106, v177
	v_mul_f32_e32 v176, v103, v101
	v_mul_f32_e32 v177, v107, v178
	v_mul_f32_e32 v178, v104, v102
	v_mul_f32_e32 v179, v108, v179
	v_pk_mul_f32 v[16:17], v[16:17], v[182:183]
	v_pk_mul_f32 v[14:15], v[14:15], v[180:181]
	v_pk_mul_f32 v[12:13], v[12:13], v[178:179]
	v_pk_mul_f32 v[10:11], v[10:11], v[176:177]
	s_cbranch_vccnz .LBB0_1146
	v_lshl_add_u64 v[84:85], v[80:81], 1, v[84:85]
	v_cvt_pk_bf16_f32 v180, v14, v15
	v_cvt_pk_bf16_f32 v181, v16, v17
	v_cvt_pk_bf16_f32 v182, v10, v11
	v_cvt_pk_bf16_f32 v183, v12, v13
	global_store_dwordx4 v[84:85], v[180:183], off offset:256
.LBB0_1146:
	s_nop 1
	v_add3_u32 v88, v92, s13, 48
	v_mov_b64_e32 v[84:85], s[8:9]
	v_mad_i64_i32 v[84:85], s[28:29], v88, s85, v[84:85]
	v_lshl_add_u64 v[86:87], v[84:85], 0, s[88:89]
	s_mov_b32 s27, s87
	v_lshl_add_u64 v[84:85], v[86:87], 0, s[86:87]
	v_lshl_add_u64 v[86:87], v[86:87], 0, s[26:27]
	v_lshl_add_u64 v[84:85], v[84:85], 0, v[82:83]
	v_lshl_add_u64 v[86:87], v[86:87], 0, v[82:83]
	global_load_dwordx4 v[92:95], v[84:85], off
	global_load_dwordx4 v[96:99], v[86:87], off
	global_load_dwordx4 v[176:179], v[84:85], off offset:256
	global_load_dwordx4 v[180:183], v[86:87], off offset:256
	v_ashrrev_i32_e32 v89, 31, v88
	v_lshlrev_b64 v[82:83], 11, v[88:89]
	s_and_b64 vcc, exec, s[4:5]
	v_lshl_add_u64 v[82:83], s[10:11], 0, v[82:83]
	s_waitcnt vmcnt(2)
	v_lshlrev_b32_e32 v102, 16, v94
	v_lshlrev_b32_e32 v100, 16, v96
	v_and_b32_e32 v96, 0xffff0000, v96
	v_lshlrev_b32_e32 v101, 16, v97
	v_and_b32_e32 v97, 0xffff0000, v97
	v_and_b32_e32 v103, 0xffff0000, v94
	v_lshlrev_b32_e32 v104, 16, v95
	v_and_b32_e32 v105, 0xffff0000, v95
	v_lshlrev_b32_e32 v94, 16, v98
	v_and_b32_e32 v95, 0xffff0000, v98
	v_lshlrev_b32_e32 v98, 16, v99
	v_and_b32_e32 v99, 0xffff0000, v99
	v_max_f32_e32 v100, 0x1e3ce508, v100
	v_max_f32_e32 v96, 0x1e3ce508, v96
	v_max_f32_e32 v101, 0x1e3ce508, v101
	v_max_f32_e32 v97, 0x1e3ce508, v97
	v_max_f32_e32 v94, 0x1e3ce508, v94
	v_max_f32_e32 v95, 0x1e3ce508, v95
	v_max_f32_e32 v98, 0x1e3ce508, v98
	v_max_f32_e32 v99, 0x1e3ce508, v99
	v_rcp_f32_e32 v100, v100
	v_rcp_f32_e32 v96, v96
	v_rcp_f32_e32 v101, v101
	v_rcp_f32_e32 v97, v97
	v_rcp_f32_e32 v94, v94
	v_rcp_f32_e32 v95, v95
	v_rcp_f32_e32 v98, v98
	v_rcp_f32_e32 v99, v99
	v_lshlrev_b32_e32 v88, 16, v92
	v_and_b32_e32 v89, 0xffff0000, v92
	v_lshlrev_b32_e32 v92, 16, v93
	v_and_b32_e32 v93, 0xffff0000, v93
	v_cndmask_b32_e64 v100, v100, 1.0, s[20:21]
	v_cndmask_b32_e64 v96, v96, 1.0, s[20:21]
	v_cndmask_b32_e64 v101, v101, 1.0, s[20:21]
	v_cndmask_b32_e64 v97, v97, 1.0, s[20:21]
	v_cndmask_b32_e64 v94, v94, 1.0, s[20:21]
	v_cndmask_b32_e64 v95, v95, 1.0, s[20:21]
	v_cndmask_b32_e64 v98, v98, 1.0, s[20:21]
	v_cndmask_b32_e64 v99, v99, 1.0, s[20:21]
	v_mul_f32_e32 v88, v100, v88
	v_mul_f32_e32 v89, v96, v89
	v_mul_f32_e32 v92, v101, v92
	v_mul_f32_e32 v93, v97, v93
	v_mul_f32_e32 v94, v94, v102
	v_mul_f32_e32 v95, v95, v103
	v_mul_f32_e32 v96, v98, v104
	v_mul_f32_e32 v97, v99, v105
	v_pk_mul_f32 v[40:41], v[40:41], v[92:93]
	v_pk_mul_f32 v[38:39], v[38:39], v[88:89]
	v_pk_mul_f32 v[36:37], v[36:37], v[96:97]
	v_pk_mul_f32 v[34:35], v[34:35], v[94:95]
	s_waitcnt vmcnt(0)
	s_cbranch_vccnz .LBB0_1148
	v_lshl_add_u64 v[88:89], v[80:81], 1, v[82:83]
	v_cvt_pk_bf16_f32 v92, v38, v39
	v_cvt_pk_bf16_f32 v93, v40, v41
	v_cvt_pk_bf16_f32 v94, v34, v35
	v_cvt_pk_bf16_f32 v95, v36, v37
	global_store_dwordx4 v[88:89], v[92:95], off
.LBB0_1148:
	s_and_b64 vcc, exec, s[4:5]
	v_lshlrev_b32_e32 v88, 16, v176
	v_lshlrev_b32_e32 v96, 16, v180
	v_and_b32_e32 v180, 0xffff0000, v180
	v_lshlrev_b32_e32 v97, 16, v181
	v_and_b32_e32 v181, 0xffff0000, v181
	v_lshlrev_b32_e32 v100, 16, v182
	v_and_b32_e32 v182, 0xffff0000, v182
	v_lshlrev_b32_e32 v101, 16, v183
	v_and_b32_e32 v183, 0xffff0000, v183
	v_max_f32_e32 v96, 0x1e3ce508, v96
	v_max_f32_e32 v180, 0x1e3ce508, v180
	v_max_f32_e32 v97, 0x1e3ce508, v97
	v_max_f32_e32 v181, 0x1e3ce508, v181
	v_max_f32_e32 v100, 0x1e3ce508, v100
	v_max_f32_e32 v182, 0x1e3ce508, v182
	v_max_f32_e32 v101, 0x1e3ce508, v101
	v_max_f32_e32 v183, 0x1e3ce508, v183
	v_rcp_f32_e32 v96, v96
	v_rcp_f32_e32 v180, v180
	v_rcp_f32_e32 v97, v97
	v_rcp_f32_e32 v181, v181
	v_rcp_f32_e32 v100, v100
	v_rcp_f32_e32 v182, v182
	v_rcp_f32_e32 v101, v101
	v_rcp_f32_e32 v183, v183
	v_and_b32_e32 v89, 0xffff0000, v176
	v_lshlrev_b32_e32 v176, 16, v177
	v_and_b32_e32 v177, 0xffff0000, v177
	v_lshlrev_b32_e32 v98, 16, v178
	v_and_b32_e32 v178, 0xffff0000, v178
	v_lshlrev_b32_e32 v99, 16, v179
	v_and_b32_e32 v179, 0xffff0000, v179
	v_cndmask_b32_e64 v96, v96, 1.0, s[20:21]
	v_cndmask_b32_e64 v102, v180, 1.0, s[20:21]
	v_cndmask_b32_e64 v97, v97, 1.0, s[20:21]
	v_cndmask_b32_e64 v103, v181, 1.0, s[20:21]
	v_cndmask_b32_e64 v100, v100, 1.0, s[20:21]
	v_cndmask_b32_e64 v104, v182, 1.0, s[20:21]
	v_cndmask_b32_e64 v101, v101, 1.0, s[20:21]
	v_cndmask_b32_e64 v105, v183, 1.0, s[20:21]
	v_mul_f32_e32 v180, v96, v88
	v_mul_f32_e32 v181, v102, v89
	v_mul_f32_e32 v182, v97, v176
	v_mul_f32_e32 v183, v103, v177
	v_mul_f32_e32 v88, v100, v98
	v_mul_f32_e32 v89, v104, v178
	v_mul_f32_e32 v176, v101, v99
	v_mul_f32_e32 v177, v105, v179
	v_pk_mul_f32 v[8:9], v[8:9], v[182:183]
	v_pk_mul_f32 v[6:7], v[6:7], v[180:181]
	v_pk_mul_f32 v[4:5], v[4:5], v[176:177]
	v_pk_mul_f32 v[2:3], v[2:3], v[88:89]
	s_cbranch_vccnz .LBB0_1150
	v_lshl_add_u64 v[80:81], v[80:81], 1, v[82:83]
	v_cvt_pk_bf16_f32 v180, v6, v7
	v_cvt_pk_bf16_f32 v181, v8, v9
	v_cvt_pk_bf16_f32 v182, v2, v3
	v_cvt_pk_bf16_f32 v183, v4, v5
	global_store_dwordx4 v[80:81], v[180:183], off offset:256

.LBB0_1479:
	v_mbcnt_lo_u32_b32 v0, -1, 0
	v_mbcnt_hi_u32_b32 v0, -1, v0
	s_lshl_b32 s21, s47, 8
	s_add_i32 s21, s21, s42
	v_and_or_b32 v134, v0, 15, s21
	v_ashrrev_i32_e32 v0, 1, v0
	v_and_b32_e32 v138, -8, v0
	s_mov_b32 s98, 0xbfb8aa3b
	v_pk_mul_f32 v[156:157], v[126:127], s[98:99] op_sel_hi:[1,0]
	v_pk_mul_f32 v[158:159], v[128:129], s[98:99] op_sel_hi:[1,0]
	v_pk_mul_f32 v[160:161], v[118:119], s[98:99] op_sel_hi:[1,0]
	v_pk_mul_f32 v[162:163], v[120:121], s[98:99] op_sel_hi:[1,0]
	v_exp_f32_e32 v156, v156
	v_exp_f32_e32 v157, v157
	v_exp_f32_e32 v158, v158
	v_exp_f32_e32 v159, v159
	v_exp_f32_e32 v160, v160
	v_exp_f32_e32 v161, v161
	v_exp_f32_e32 v162, v162
	v_exp_f32_e32 v163, v163
	v_pk_add_f32 v[156:157], v[156:157], 1.0 op_sel_hi:[1,0]
	v_pk_add_f32 v[158:159], v[158:159], 1.0 op_sel_hi:[1,0]
	v_pk_add_f32 v[160:161], v[160:161], 1.0 op_sel_hi:[1,0]
	v_pk_add_f32 v[162:163], v[162:163], 1.0 op_sel_hi:[1,0]
	v_rcp_f32_e32 v156, v156
	v_rcp_f32_e32 v157, v157
	v_rcp_f32_e32 v158, v158
	v_rcp_f32_e32 v159, v159
	v_rcp_f32_e32 v160, v160
	v_rcp_f32_e32 v161, v161
	v_rcp_f32_e32 v162, v162
	v_rcp_f32_e32 v163, v163
	v_pk_mul_f32 v[156:157], v[126:127], v[156:157]
	v_pk_mul_f32 v[158:159], v[128:129], v[158:159]
	v_pk_mul_f32 v[160:161], v[118:119], v[160:161]
	v_pk_mul_f32 v[162:163], v[120:121], v[162:163]
	v_mul_f32_e32 v0, v156, v122
	v_mul_f32_e32 v122, v157, v123
	v_mul_f32_e32 v123, v158, v124
	v_mul_f32_e32 v124, v159, v125
	v_mul_f32_e32 v118, v160, v114
	v_mul_f32_e32 v119, v161, v115
	v_mul_f32_e32 v125, v162, v116
	v_mul_f32_e32 v126, v163, v117
	s_lshl_b32 s26, s48, 7
	v_ashrrev_i32_e32 v135, 31, v134
	s_ashr_i32 s27, s26, 31
	v_lshlrev_b64 v[140:141], 11, v[134:135]
	v_lshl_add_u64 v[140:141], s[14:15], 0, v[140:141]
	s_lshl_b64 s[26:27], s[26:27], 1
	v_ashrrev_i32_e32 v139, 31, v138
	v_lshl_add_u64 v[140:141], v[140:141], 0, s[26:27]
	v_lshl_add_u64 v[140:141], v[140:141], 0, s[86:87]
	s_and_b64 vcc, exec, s[6:7]
	v_cvt_pk_bf16_f32 v118, v118, v119
	s_nop 0
	v_cvt_pk_bf16_f32 v116, v0, v122
	s_mov_b32 s98, 0xbfb8aa3b
	v_pk_mul_f32 v[156:157], v[110:111], s[98:99] op_sel_hi:[1,0]
	v_pk_mul_f32 v[158:159], v[112:113], s[98:99] op_sel_hi:[1,0]
	v_pk_mul_f32 v[160:161], v[102:103], s[98:99] op_sel_hi:[1,0]
	v_pk_mul_f32 v[162:163], v[104:105], s[98:99] op_sel_hi:[1,0]
	v_exp_f32_e32 v156, v156
	v_exp_f32_e32 v157, v157
	v_exp_f32_e32 v158, v158
	v_exp_f32_e32 v159, v159
	v_exp_f32_e32 v160, v160
	v_exp_f32_e32 v161, v161
	v_exp_f32_e32 v162, v162
	v_exp_f32_e32 v163, v163
	v_pk_add_f32 v[156:157], v[156:157], 1.0 op_sel_hi:[1,0]
	v_pk_add_f32 v[158:159], v[158:159], 1.0 op_sel_hi:[1,0]
	v_pk_add_f32 v[160:161], v[160:161], 1.0 op_sel_hi:[1,0]
	v_pk_add_f32 v[162:163], v[162:163], 1.0 op_sel_hi:[1,0]
	v_rcp_f32_e32 v156, v156
	v_rcp_f32_e32 v157, v157
	v_rcp_f32_e32 v158, v158
	v_rcp_f32_e32 v159, v159
	v_rcp_f32_e32 v160, v160
	v_rcp_f32_e32 v161, v161
	v_rcp_f32_e32 v162, v162
	v_rcp_f32_e32 v163, v163
	v_pk_mul_f32 v[156:157], v[110:111], v[156:157]
	v_pk_mul_f32 v[158:159], v[112:113], v[158:159]
	v_pk_mul_f32 v[160:161], v[102:103], v[160:161]
	v_pk_mul_f32 v[162:163], v[104:105], v[162:163]
	v_mul_f32_e32 v0, v156, v106
	v_mul_f32_e32 v106, v157, v107
	v_mul_f32_e32 v107, v158, v108
	v_mul_f32_e32 v108, v159, v109
	v_mul_f32_e32 v109, v160, v98
	v_mul_f32_e32 v110, v161, v99
	v_mul_f32_e32 v104, v162, v100
	v_mul_f32_e32 v101, v163, v101
	v_lshlrev_b64 v[114:115], 1, v[138:139]
	v_lshl_add_u64 v[120:121], v[140:141], 0, v[114:115]
	v_cvt_pk_bf16_f32 v117, v123, v124
	v_cvt_pk_bf16_f32 v119, v125, v126
	global_store_dwordx4 v[120:121], v[116:119], off
	s_nop 1
	v_or_b32_e32 v116, 16, v134
	v_ashrrev_i32_e32 v117, 31, v116
	v_lshlrev_b64 v[116:117], 11, v[116:117]
	v_lshl_add_u64 v[116:117], s[14:15], 0, v[116:117]
	v_lshl_add_u64 v[116:117], v[116:117], 0, s[26:27]
	v_lshl_add_u64 v[116:117], v[116:117], 0, s[86:87]
	v_lshl_add_u64 v[102:103], v[116:117], 0, v[114:115]
	v_cvt_pk_bf16_f32 v99, v107, v108
	v_cvt_pk_bf16_f32 v100, v109, v110
	s_nop 0
	v_cvt_pk_bf16_f32 v98, v0, v106
	s_mov_b32 s98, 0xbfb8aa3b
	v_pk_mul_f32 v[156:157], v[94:95], s[98:99] op_sel_hi:[1,0]
	v_pk_mul_f32 v[158:159], v[96:97], s[98:99] op_sel_hi:[1,0]
	v_pk_mul_f32 v[160:161], v[86:87], s[98:99] op_sel_hi:[1,0]
	v_pk_mul_f32 v[162:163], v[88:89], s[98:99] op_sel_hi:[1,0]
	v_exp_f32_e32 v156, v156
	v_exp_f32_e32 v157, v157
	v_exp_f32_e32 v158, v158
	v_exp_f32_e32 v159, v159
	v_exp_f32_e32 v160, v160
	v_exp_f32_e32 v161, v161
	v_exp_f32_e32 v162, v162
	v_exp_f32_e32 v163, v163
	v_pk_add_f32 v[156:157], v[156:157], 1.0 op_sel_hi:[1,0]
	v_pk_add_f32 v[158:159], v[158:159], 1.0 op_sel_hi:[1,0]
	v_pk_add_f32 v[160:161], v[160:161], 1.0 op_sel_hi:[1,0]
	v_pk_add_f32 v[162:163], v[162:163], 1.0 op_sel_hi:[1,0]
	v_rcp_f32_e32 v156, v156
	v_rcp_f32_e32 v157, v157
	v_rcp_f32_e32 v158, v158
	v_rcp_f32_e32 v159, v159
	v_rcp_f32_e32 v160, v160
	v_rcp_f32_e32 v161, v161
	v_rcp_f32_e32 v162, v162
	v_rcp_f32_e32 v163, v163
	v_pk_mul_f32 v[156:157], v[94:95], v[156:157]
	v_pk_mul_f32 v[158:159], v[96:97], v[158:159]
	v_pk_mul_f32 v[160:161], v[86:87], v[160:161]
	v_pk_mul_f32 v[162:163], v[88:89], v[162:163]
	v_mul_f32_e32 v0, v156, v90
	v_mul_f32_e32 v90, v157, v91
	v_mul_f32_e32 v91, v158, v92
	v_mul_f32_e32 v92, v159, v93
	v_mul_f32_e32 v93, v160, v82
	v_mul_f32_e32 v94, v161, v83
	v_mul_f32_e32 v88, v162, v84
	v_mul_f32_e32 v85, v163, v85
	v_cvt_pk_bf16_f32 v101, v104, v101
	global_store_dwordx4 v[102:103], v[98:101], off
	s_nop 1
	v_or_b32_e32 v98, 32, v134
	v_ashrrev_i32_e32 v99, 31, v98
	v_lshlrev_b64 v[98:99], 11, v[98:99]
	v_lshl_add_u64 v[98:99], s[14:15], 0, v[98:99]
	v_lshl_add_u64 v[98:99], v[98:99], 0, s[26:27]
	v_lshl_add_u64 v[98:99], v[98:99], 0, s[86:87]
	v_lshl_add_u64 v[86:87], v[98:99], 0, v[114:115]
	v_cvt_pk_bf16_f32 v83, v91, v92
	v_cvt_pk_bf16_f32 v84, v93, v94
	s_nop 0
	v_cvt_pk_bf16_f32 v82, v0, v90
	s_mov_b32 s98, 0xbfb8aa3b
	v_pk_mul_f32 v[156:157], v[78:79], s[98:99] op_sel_hi:[1,0]
	v_pk_mul_f32 v[158:159], v[80:81], s[98:99] op_sel_hi:[1,0]
	v_pk_mul_f32 v[160:161], v[70:71], s[98:99] op_sel_hi:[1,0]
	v_pk_mul_f32 v[162:163], v[72:73], s[98:99] op_sel_hi:[1,0]
	v_exp_f32_e32 v156, v156
	v_exp_f32_e32 v157, v157
	v_exp_f32_e32 v158, v158
	v_exp_f32_e32 v159, v159
	v_exp_f32_e32 v160, v160
	v_exp_f32_e32 v161, v161
	v_exp_f32_e32 v162, v162
	v_exp_f32_e32 v163, v163
	v_pk_add_f32 v[156:157], v[156:157], 1.0 op_sel_hi:[1,0]
	v_pk_add_f32 v[158:159], v[158:159], 1.0 op_sel_hi:[1,0]
	v_pk_add_f32 v[160:161], v[160:161], 1.0 op_sel_hi:[1,0]
	v_pk_add_f32 v[162:163], v[162:163], 1.0 op_sel_hi:[1,0]
	v_rcp_f32_e32 v156, v156
	v_rcp_f32_e32 v157, v157
	v_rcp_f32_e32 v158, v158
	v_rcp_f32_e32 v159, v159
	v_rcp_f32_e32 v160, v160
	v_rcp_f32_e32 v161, v161
	v_rcp_f32_e32 v162, v162
	v_rcp_f32_e32 v163, v163
	v_pk_mul_f32 v[156:157], v[78:79], v[156:157]
	v_pk_mul_f32 v[158:159], v[80:81], v[158:159]
	v_pk_mul_f32 v[160:161], v[70:71], v[160:161]
	v_pk_mul_f32 v[162:163], v[72:73], v[162:163]
	v_mul_f32_e32 v0, v156, v74
	v_mul_f32_e32 v74, v157, v75
	v_mul_f32_e32 v75, v158, v76
	v_mul_f32_e32 v76, v159, v77
	v_mul_f32_e32 v77, v160, v66
	v_mul_f32_e32 v78, v161, v67
	v_mul_f32_e32 v72, v162, v68
	v_mul_f32_e32 v69, v163, v69
	v_cvt_pk_bf16_f32 v85, v88, v85
	global_store_dwordx4 v[86:87], v[82:85], off
	s_nop 1
	v_or_b32_e32 v82, 48, v134
	v_ashrrev_i32_e32 v83, 31, v82
	v_lshlrev_b64 v[82:83], 11, v[82:83]
	v_lshl_add_u64 v[82:83], s[14:15], 0, v[82:83]
	v_lshl_add_u64 v[82:83], v[82:83], 0, s[26:27]
	v_lshl_add_u64 v[82:83], v[82:83], 0, s[86:87]
	v_lshl_add_u64 v[70:71], v[82:83], 0, v[114:115]
	v_cvt_pk_bf16_f32 v67, v75, v76
	v_cvt_pk_bf16_f32 v68, v77, v78
	s_nop 0
	v_cvt_pk_bf16_f32 v66, v0, v74
	s_mov_b32 s98, 0xbfb8aa3b
	v_pk_mul_f32 v[156:157], v[62:63], s[98:99] op_sel_hi:[1,0]
	v_pk_mul_f32 v[158:159], v[64:65], s[98:99] op_sel_hi:[1,0]
	v_pk_mul_f32 v[160:161], v[54:55], s[98:99] op_sel_hi:[1,0]
	v_pk_mul_f32 v[162:163], v[56:57], s[98:99] op_sel_hi:[1,0]
	v_exp_f32_e32 v156, v156
	v_exp_f32_e32 v157, v157
	v_exp_f32_e32 v158, v158
	v_exp_f32_e32 v159, v159
	v_exp_f32_e32 v160, v160
	v_exp_f32_e32 v161, v161
	v_exp_f32_e32 v162, v162
	v_exp_f32_e32 v163, v163
	v_pk_add_f32 v[156:157], v[156:157], 1.0 op_sel_hi:[1,0]
	v_pk_add_f32 v[158:159], v[158:159], 1.0 op_sel_hi:[1,0]
	v_pk_add_f32 v[160:161], v[160:161], 1.0 op_sel_hi:[1,0]
	v_pk_add_f32 v[162:163], v[162:163], 1.0 op_sel_hi:[1,0]
	v_rcp_f32_e32 v156, v156
	v_rcp_f32_e32 v157, v157
	v_rcp_f32_e32 v158, v158
	v_rcp_f32_e32 v159, v159
	v_rcp_f32_e32 v160, v160
	v_rcp_f32_e32 v161, v161
	v_rcp_f32_e32 v162, v162
	v_rcp_f32_e32 v163, v163
	v_pk_mul_f32 v[156:157], v[62:63], v[156:157]
	v_pk_mul_f32 v[158:159], v[64:65], v[158:159]
	v_pk_mul_f32 v[160:161], v[54:55], v[160:161]
	v_pk_mul_f32 v[162:163], v[56:57], v[162:163]
	v_mul_f32_e32 v0, v156, v58
	v_mul_f32_e32 v58, v157, v59
	v_mul_f32_e32 v59, v158, v60
	v_mul_f32_e32 v60, v159, v61
	v_mul_f32_e32 v61, v160, v50
	v_mul_f32_e32 v62, v161, v51
	v_mul_f32_e32 v56, v162, v52
	v_mul_f32_e32 v53, v163, v53
	v_cvt_pk_bf16_f32 v69, v72, v69
	global_store_dwordx4 v[70:71], v[66:69], off
	s_nop 1
	v_add_u32_e32 v66, 0x80, v134
	v_ashrrev_i32_e32 v67, 31, v66
	v_lshlrev_b64 v[66:67], 11, v[66:67]
	v_lshl_add_u64 v[66:67], s[14:15], 0, v[66:67]
	v_lshl_add_u64 v[66:67], v[66:67], 0, s[26:27]
	v_lshl_add_u64 v[66:67], v[66:67], 0, s[86:87]
	v_lshl_add_u64 v[54:55], v[66:67], 0, v[114:115]
	v_cvt_pk_bf16_f32 v51, v59, v60
	v_cvt_pk_bf16_f32 v52, v61, v62
	s_nop 0
	v_cvt_pk_bf16_f32 v50, v0, v58
	s_mov_b32 s98, 0xbfb8aa3b
	v_pk_mul_f32 v[156:157], v[46:47], s[98:99] op_sel_hi:[1,0]
	v_pk_mul_f32 v[158:159], v[48:49], s[98:99] op_sel_hi:[1,0]
	v_pk_mul_f32 v[160:161], v[38:39], s[98:99] op_sel_hi:[1,0]
	v_pk_mul_f32 v[162:163], v[40:41], s[98:99] op_sel_hi:[1,0]
	v_exp_f32_e32 v156, v156
	v_exp_f32_e32 v157, v157
	v_exp_f32_e32 v158, v158
	v_exp_f32_e32 v159, v159
	v_exp_f32_e32 v160, v160
	v_exp_f32_e32 v161, v161
	v_exp_f32_e32 v162, v162
	v_exp_f32_e32 v163, v163
	v_pk_add_f32 v[156:157], v[156:157], 1.0 op_sel_hi:[1,0]
	v_pk_add_f32 v[158:159], v[158:159], 1.0 op_sel_hi:[1,0]
	v_pk_add_f32 v[160:161], v[160:161], 1.0 op_sel_hi:[1,0]
	v_pk_add_f32 v[162:163], v[162:163], 1.0 op_sel_hi:[1,0]
	v_rcp_f32_e32 v156, v156
	v_rcp_f32_e32 v157, v157
	v_rcp_f32_e32 v158, v158
	v_rcp_f32_e32 v159, v159
	v_rcp_f32_e32 v160, v160
	v_rcp_f32_e32 v161, v161
	v_rcp_f32_e32 v162, v162
	v_rcp_f32_e32 v163, v163
	v_pk_mul_f32 v[156:157], v[46:47], v[156:157]
	v_pk_mul_f32 v[158:159], v[48:49], v[158:159]
	v_pk_mul_f32 v[160:161], v[38:39], v[160:161]
	v_pk_mul_f32 v[162:163], v[40:41], v[162:163]
	v_mul_f32_e32 v0, v156, v42
	v_mul_f32_e32 v42, v157, v43
	v_mul_f32_e32 v43, v158, v44
	v_mul_f32_e32 v44, v159, v45
	v_mul_f32_e32 v45, v160, v34
	v_mul_f32_e32 v46, v161, v35
	v_mul_f32_e32 v40, v162, v36
	v_mul_f32_e32 v37, v163, v37
	v_cvt_pk_bf16_f32 v53, v56, v53
	global_store_dwordx4 v[54:55], v[50:53], off
	s_nop 1
	v_add_u32_e32 v50, 0x90, v134
	v_ashrrev_i32_e32 v51, 31, v50
	v_lshlrev_b64 v[50:51], 11, v[50:51]
	v_lshl_add_u64 v[50:51], s[14:15], 0, v[50:51]
	v_lshl_add_u64 v[50:51], v[50:51], 0, s[26:27]
	v_lshl_add_u64 v[50:51], v[50:51], 0, s[86:87]
	v_lshl_add_u64 v[38:39], v[50:51], 0, v[114:115]
	v_cvt_pk_bf16_f32 v35, v43, v44
	v_cvt_pk_bf16_f32 v36, v45, v46
	s_nop 0
	v_cvt_pk_bf16_f32 v34, v0, v42
	s_mov_b32 s98, 0xbfb8aa3b
	v_pk_mul_f32 v[156:157], v[30:31], s[98:99] op_sel_hi:[1,0]
	v_pk_mul_f32 v[158:159], v[32:33], s[98:99] op_sel_hi:[1,0]
	v_pk_mul_f32 v[160:161], v[22:23], s[98:99] op_sel_hi:[1,0]
	v_pk_mul_f32 v[162:163], v[24:25], s[98:99] op_sel_hi:[1,0]
	v_exp_f32_e32 v156, v156
	v_exp_f32_e32 v157, v157
	v_exp_f32_e32 v158, v158
	v_exp_f32_e32 v159, v159
	v_exp_f32_e32 v160, v160
	v_exp_f32_e32 v161, v161
	v_exp_f32_e32 v162, v162
	v_exp_f32_e32 v163, v163
	v_pk_add_f32 v[156:157], v[156:157], 1.0 op_sel_hi:[1,0]
	v_pk_add_f32 v[158:159], v[158:159], 1.0 op_sel_hi:[1,0]
	v_pk_add_f32 v[160:161], v[160:161], 1.0 op_sel_hi:[1,0]
	v_pk_add_f32 v[162:163], v[162:163], 1.0 op_sel_hi:[1,0]
	v_rcp_f32_e32 v156, v156
	v_rcp_f32_e32 v157, v157
	v_rcp_f32_e32 v158, v158
	v_rcp_f32_e32 v159, v159
	v_rcp_f32_e32 v160, v160
	v_rcp_f32_e32 v161, v161
	v_rcp_f32_e32 v162, v162
	v_rcp_f32_e32 v163, v163
	v_pk_mul_f32 v[156:157], v[30:31], v[156:157]
	v_pk_mul_f32 v[158:159], v[32:33], v[158:159]
	v_pk_mul_f32 v[160:161], v[22:23], v[160:161]
	v_pk_mul_f32 v[162:163], v[24:25], v[162:163]
	v_mul_f32_e32 v0, v156, v26
	v_mul_f32_e32 v26, v157, v27
	v_mul_f32_e32 v27, v158, v28
	v_mul_f32_e32 v28, v159, v29
	v_mul_f32_e32 v29, v160, v18
	v_mul_f32_e32 v30, v161, v19
	v_mul_f32_e32 v24, v162, v20
	v_mul_f32_e32 v21, v163, v21
	v_cvt_pk_bf16_f32 v37, v40, v37
	global_store_dwordx4 v[38:39], v[34:37], off
	s_nop 1
	v_add_u32_e32 v34, 0xa0, v134
	v_ashrrev_i32_e32 v35, 31, v34
	v_lshlrev_b64 v[34:35], 11, v[34:35]
	v_lshl_add_u64 v[34:35], s[14:15], 0, v[34:35]
	v_lshl_add_u64 v[34:35], v[34:35], 0, s[26:27]
	v_lshl_add_u64 v[34:35], v[34:35], 0, s[86:87]
	v_lshl_add_u64 v[22:23], v[34:35], 0, v[114:115]
	v_cvt_pk_bf16_f32 v19, v27, v28
	v_cvt_pk_bf16_f32 v20, v29, v30
	s_nop 0
	v_cvt_pk_bf16_f32 v18, v0, v26
	s_mov_b32 s98, 0xbfb8aa3b
	v_pk_mul_f32 v[156:157], v[14:15], s[98:99] op_sel_hi:[1,0]
	v_pk_mul_f32 v[158:159], v[16:17], s[98:99] op_sel_hi:[1,0]
	v_pk_mul_f32 v[160:161], v[6:7], s[98:99] op_sel_hi:[1,0]
	v_pk_mul_f32 v[162:163], v[8:9], s[98:99] op_sel_hi:[1,0]
	v_exp_f32_e32 v156, v156
	v_exp_f32_e32 v157, v157
	v_exp_f32_e32 v158, v158
	v_exp_f32_e32 v159, v159
	v_exp_f32_e32 v160, v160
	v_exp_f32_e32 v161, v161
	v_exp_f32_e32 v162, v162
	v_exp_f32_e32 v163, v163
	v_pk_add_f32 v[156:157], v[156:157], 1.0 op_sel_hi:[1,0]
	v_pk_add_f32 v[158:159], v[158:159], 1.0 op_sel_hi:[1,0]
	v_pk_add_f32 v[160:161], v[160:161], 1.0 op_sel_hi:[1,0]
	v_pk_add_f32 v[162:163], v[162:163], 1.0 op_sel_hi:[1,0]
	v_rcp_f32_e32 v156, v156
	v_rcp_f32_e32 v157, v157
	v_rcp_f32_e32 v158, v158
	v_rcp_f32_e32 v159, v159
	v_rcp_f32_e32 v160, v160
	v_rcp_f32_e32 v161, v161
	v_rcp_f32_e32 v162, v162
	v_rcp_f32_e32 v163, v163
	v_pk_mul_f32 v[156:157], v[14:15], v[156:157]
	v_pk_mul_f32 v[158:159], v[16:17], v[158:159]
	v_pk_mul_f32 v[160:161], v[6:7], v[160:161]
	v_pk_mul_f32 v[162:163], v[8:9], v[162:163]
	v_mul_f32_e32 v0, v156, v10
	v_mul_f32_e32 v10, v157, v11
	v_mul_f32_e32 v11, v158, v12
	v_mul_f32_e32 v12, v159, v13
	v_mul_f32_e32 v13, v160, v2
	v_mul_f32_e32 v14, v161, v3
	v_mul_f32_e32 v8, v162, v4
	v_mul_f32_e32 v5, v163, v5
	v_cvt_pk_bf16_f32 v21, v24, v21
	global_store_dwordx4 v[22:23], v[18:21], off
	s_nop 1
	v_add_u32_e32 v18, 0xb0, v134
	v_ashrrev_i32_e32 v19, 31, v18
	v_lshlrev_b64 v[18:19], 11, v[18:19]
	v_lshl_add_u64 v[18:19], s[14:15], 0, v[18:19]
	v_lshl_add_u64 v[18:19], v[18:19], 0, s[26:27]
	v_lshl_add_u64 v[18:19], v[18:19], 0, s[86:87]
	s_mov_b64 s[26:27], -1
	v_lshl_add_u64 v[6:7], v[18:19], 0, v[114:115]
	v_cvt_pk_bf16_f32 v3, v11, v12
	v_cvt_pk_bf16_f32 v4, v13, v14
	s_nop 0
	v_cvt_pk_bf16_f32 v2, v0, v10
	v_cvt_pk_bf16_f32 v5, v8, v5
	global_store_dwordx4 v[6:7], v[2:5], off
	s_cbranch_vccnz .LBB0_1467
	s_andn2_b64 vcc, exec, s[12:13]
	s_cbranch_vccnz .LBB0_1466
	s_barrier
	s_branch .LBB0_1466
